# nontemporal (nt) loads for the read-once f32 weights in the transposes so the conversion running beside the last G1 round does not evict the GEMM operands from L2
# speedup vs baseline: 1.0090x; 1.0090x over previous
; #define LDS_WAIT() asm volatile("s_waitcnt lgkmcnt(0)" ::: "memory")
;     ...
; #pragma unroll 8
;     for (int i = 0; i < 32; ++i) { const int kk = 2 * i + (lane >> 5); scr[kk * 33 + (lane & 31)] = W[(size_t)(k0 + kk) * N + n0 + (lane & 31)]; }
;     LDS_WAIT(); asm volatile("" ::: "memory");
.LBB0_475:
	s_lshl_b32 s45, s3, 1
	s_lshl_b32 s46, s43, 1
	v_or_b32_e32 v0, s46, v2
	s_add_i32 s48, s45, 4
	s_add_i32 s49, s46, 4
	v_mov_b32_e32 v23, v1
	s_add_i32 s50, s45, 8
	s_add_i32 s51, s46, 8
	s_add_i32 s53, s46, 12
	s_add_i32 s55, s46, 16
	s_add_i32 s56, s45, 20
	s_add_i32 s57, s46, 20
	s_add_i32 s58, s45, 24
	s_add_i32 s59, s46, 24
	s_add_i32 s60, s46, 28
	v_lshlrev_b64 v[40:41], 12, v[0:1]
	v_mad_u64_u32 v[42:43], s[46:47], v0, s85, v[6:7]
	v_or_b32_e32 v22, s48, v3
	v_or_b32_e32 v0, s49, v2
	v_mov_b32_e32 v17, v1
	v_mov_b32_e32 v25, v1
	v_mov_b32_e32 v31, v1
	v_mov_b32_e32 v33, v1
	v_or_b32_e32 v16, s45, v3
	s_add_i32 s52, s45, 12
	s_add_i32 s54, s45, 16
	s_add_i32 s45, s45, 28
	v_or_b32_e32 v24, s50, v3
	v_or_b32_e32 v30, s56, v3
	v_or_b32_e32 v32, s58, v3
	v_lshlrev_b64 v[44:45], 12, v[22:23]
	v_lshlrev_b64 v[46:47], 12, v[0:1]
	v_mad_u64_u32 v[48:49], s[46:47], v0, s85, v[6:7]
	v_or_b32_e32 v0, s51, v2
	v_mov_b32_e32 v27, v1
	v_mov_b32_e32 v29, v1
	v_mov_b32_e32 v35, v1
	v_lshlrev_b64 v[36:37], 12, v[16:17]
	v_or_b32_e32 v26, s52, v3
	v_or_b32_e32 v28, s54, v3
	v_or_b32_e32 v34, s45, v3
	v_lshl_add_u64 v[40:41], v[14:15], 0, v[40:41]
	v_lshlrev_b64 v[50:51], 12, v[24:25]
	v_lshlrev_b64 v[56:57], 12, v[30:31]
	v_lshlrev_b64 v[58:59], 12, v[32:33]
	v_lshl_add_u64 v[44:45], v[14:15], 0, v[44:45]
	v_lshlrev_b64 v[62:63], 12, v[0:1]
	v_mad_u64_u32 v[64:65], s[46:47], v0, s85, v[6:7]
	v_or_b32_e32 v0, s53, v2
	v_lshl_add_u64 v[36:37], v[14:15], 0, v[36:37]
	v_lshlrev_b64 v[52:53], 12, v[26:27]
	v_lshlrev_b64 v[54:55], 12, v[28:29]
	v_lshlrev_b64 v[60:61], 12, v[34:35]
	v_lshl_add_u64 v[46:47], v[14:15], 0, v[46:47]
	v_lshl_add_u64 v[50:51], v[14:15], 0, v[50:51]
	v_lshl_add_u64 v[56:57], v[14:15], 0, v[56:57]
	v_lshl_add_u64 v[58:59], v[14:15], 0, v[58:59]
	global_load_dword v5, v[40:41], off nt
	global_load_dword v21, v[36:37], off nt
	global_load_dword v39, v[46:47], off nt
	global_load_dword v43, v[44:45], off nt
	v_lshlrev_b64 v[40:41], 12, v[0:1]
	v_mad_u64_u32 v[44:45], s[46:47], v0, s85, v[6:7]
	v_or_b32_e32 v0, s55, v2
	v_lshl_add_u64 v[52:53], v[14:15], 0, v[52:53]
	v_lshl_add_u64 v[54:55], v[14:15], 0, v[54:55]
	v_lshl_add_u64 v[60:61], v[14:15], 0, v[60:61]
	v_lshl_add_u64 v[36:37], v[14:15], 0, v[62:63]
	global_load_dword v45, v[50:51], off nt
	global_load_dword v49, v[52:53], off nt
	global_load_dword v62, v[54:55], off nt
	s_nop 0
	global_load_dword v56, v[56:57], off nt
	s_nop 0
	global_load_dword v57, v[58:59], off nt
	s_nop 0
	global_load_dword v58, v[60:61], off nt
	v_lshl_add_u64 v[40:41], v[14:15], 0, v[40:41]
	v_lshlrev_b64 v[46:47], 12, v[0:1]
	v_mad_u64_u32 v[50:51], s[46:47], v0, s85, v[6:7]
	v_or_b32_e32 v0, s57, v2
	global_load_dword v51, v[36:37], off nt
	global_load_dword v59, v[40:41], off nt
	v_lshl_add_u64 v[36:37], v[14:15], 0, v[46:47]
	v_lshlrev_b64 v[40:41], 12, v[0:1]
	v_mad_u64_u32 v[46:47], s[46:47], v0, s85, v[6:7]
	v_or_b32_e32 v0, s59, v2
	v_mad_u64_u32 v[54:55], s[46:47], v0, s85, v[6:7]
	v_lshl_add_u64 v[40:41], v[14:15], 0, v[40:41]
	global_load_dword v47, v[36:37], off nt
	global_load_dword v55, v[40:41], off nt
	v_lshlrev_b64 v[52:53], 12, v[0:1]
	v_or_b32_e32 v0, s60, v2
	v_lshl_add_u64 v[36:37], v[14:15], 0, v[52:53]
	v_lshlrev_b64 v[40:41], 12, v[0:1]
	global_load_dword v52, v[36:37], off nt
	v_lshl_add_u64 v[36:37], v[14:15], 0, v[40:41]
	global_load_dword v40, v[36:37], off nt
	s_add_i32 s43, s43, 16
	s_add_i32 s3, s3, 16
	s_add_i32 s44, s44, -16
	s_cmp_lg_u32 s44, 0
	v_mov_b32_e32 v95, 0
	s_lshl_b32 s45, s3, 1
	s_lshl_b32 s46, s43, 1
	v_or_b32_e32 v94, s46, v2
	s_add_i32 s48, s45, 4
	s_add_i32 s49, s46, 4
	v_mov_b32_e32 v103, v95
	s_add_i32 s50, s45, 8
	s_add_i32 s51, s46, 8
	s_add_i32 s53, s46, 12
	s_add_i32 s55, s46, 16
	s_add_i32 s56, s45, 20
	s_add_i32 s57, s46, 20
	s_add_i32 s58, s45, 24
	s_add_i32 s59, s46, 24
	s_add_i32 s60, s46, 28
	v_lshlrev_b64 v[120:121], 12, v[94:95]
	v_mad_u64_u32 v[122:123], s[46:47], v94, s85, v[6:7]
	v_or_b32_e32 v102, s48, v3
	v_or_b32_e32 v94, s49, v2
	v_mov_b32_e32 v99, v95
	v_mov_b32_e32 v105, v95
	v_mov_b32_e32 v111, v95
	v_mov_b32_e32 v113, v95
	v_or_b32_e32 v98, s45, v3
	s_add_i32 s52, s45, 12
	s_add_i32 s54, s45, 16
	s_add_i32 s45, s45, 28
	v_or_b32_e32 v104, s50, v3
	v_or_b32_e32 v110, s56, v3
	v_or_b32_e32 v112, s58, v3
	v_lshlrev_b64 v[124:125], 12, v[102:103]
	v_lshlrev_b64 v[126:127], 12, v[94:95]
	v_mad_u64_u32 v[128:129], s[46:47], v94, s85, v[6:7]
	v_or_b32_e32 v94, s51, v2
	v_mov_b32_e32 v107, v95
	v_mov_b32_e32 v109, v95
	v_mov_b32_e32 v115, v95
	v_lshlrev_b64 v[116:117], 12, v[98:99]
	v_or_b32_e32 v106, s52, v3
	v_or_b32_e32 v108, s54, v3
	v_or_b32_e32 v114, s45, v3
	v_lshl_add_u64 v[120:121], v[14:15], 0, v[120:121]
	v_lshlrev_b64 v[130:131], 12, v[104:105]
	v_lshlrev_b64 v[136:137], 12, v[110:111]
	v_lshlrev_b64 v[150:151], 12, v[112:113]
	v_lshl_add_u64 v[124:125], v[14:15], 0, v[124:125]
	v_lshlrev_b64 v[154:155], 12, v[94:95]
	v_mad_u64_u32 v[156:157], s[46:47], v94, s85, v[6:7]
	v_or_b32_e32 v94, s53, v2
	v_lshl_add_u64 v[116:117], v[14:15], 0, v[116:117]
	v_lshlrev_b64 v[132:133], 12, v[106:107]
	v_lshlrev_b64 v[134:135], 12, v[108:109]
	v_lshlrev_b64 v[152:153], 12, v[114:115]
	v_lshl_add_u64 v[126:127], v[14:15], 0, v[126:127]
	v_lshl_add_u64 v[130:131], v[14:15], 0, v[130:131]
	v_lshl_add_u64 v[136:137], v[14:15], 0, v[136:137]
	v_lshl_add_u64 v[150:151], v[14:15], 0, v[150:151]
	global_load_dword v97, v[120:121], off nt
	global_load_dword v101, v[116:117], off nt
	global_load_dword v119, v[126:127], off nt
	global_load_dword v123, v[124:125], off nt
	v_lshlrev_b64 v[120:121], 12, v[94:95]
; __device__ __forceinline__ unsigned cvt_pk_bf16(float lo, float hi) { unsigned r; asm volatile("v_cvt_pk_bf16_f32 %0, %1, %2" : "=v"(r) : "v"(lo), "v"(hi)); return r; }
; #define LAS __attribute__((address_space(3)))
; #define LDS_WAIT() asm volatile("s_waitcnt lgkmcnt(0)" ::: "memory")
;     ...
;     for (int i = 0; i < 32; ++i) { const int kk = 2 * i + (lane >> 5); scr[kk * 33 + (lane & 31)] = W[(size_t)(k0 + kk) * N + n0 + (lane & 31)]; }
;     LDS_WAIT(); asm volatile("" ::: "memory");
;     const int c = lane & 7;
; #pragma unroll
;     for (int j = 0; j < 4; ++j) { const int n = (lane >> 3) + 8 * j; const LAS float* s = scr + (8 * c) * 33 + n;
;         u32x4 o; o.x = cvt_pk_bf16(s[0 * 33], s[1 * 33]); o.y = cvt_pk_bf16(s[2 * 33], s[3 * 33]); o.z = cvt_pk_bf16(s[4 * 33], s[5 * 33]); o.w = cvt_pk_bf16(s[6 * 33], s[7 * 33]);
;         *(u32x4*)(WT + (size_t)(dn0 + n) * ldo + koff + k0 + 8 * c) = o; }
;     LDS_WAIT(); asm volatile("" ::: "memory");
	v_mad_u64_u32 v[124:125], s[46:47], v94, s85, v[6:7]
	v_or_b32_e32 v94, s55, v2
	v_lshl_add_u64 v[132:133], v[14:15], 0, v[132:133]
	v_lshl_add_u64 v[134:135], v[14:15], 0, v[134:135]
	v_lshl_add_u64 v[152:153], v[14:15], 0, v[152:153]
	v_lshl_add_u64 v[116:117], v[14:15], 0, v[154:155]
	global_load_dword v125, v[130:131], off nt
	global_load_dword v129, v[132:133], off nt
	global_load_dword v154, v[134:135], off nt
	s_nop 0
	global_load_dword v136, v[136:137], off nt
	s_nop 0
	global_load_dword v137, v[150:151], off nt
	s_nop 0
	global_load_dword v150, v[152:153], off nt
	v_lshl_add_u64 v[120:121], v[14:15], 0, v[120:121]
	v_lshlrev_b64 v[126:127], 12, v[94:95]
	v_mad_u64_u32 v[130:131], s[46:47], v94, s85, v[6:7]
	v_or_b32_e32 v94, s57, v2
	global_load_dword v131, v[116:117], off nt
	global_load_dword v151, v[120:121], off nt
	v_lshl_add_u64 v[116:117], v[14:15], 0, v[126:127]
	v_lshlrev_b64 v[120:121], 12, v[94:95]
	v_mad_u64_u32 v[126:127], s[46:47], v94, s85, v[6:7]
	v_or_b32_e32 v94, s59, v2
	v_mad_u64_u32 v[134:135], s[46:47], v94, s85, v[6:7]
	v_lshl_add_u64 v[120:121], v[14:15], 0, v[120:121]
	global_load_dword v127, v[116:117], off nt
	global_load_dword v135, v[120:121], off nt
	v_lshlrev_b64 v[132:133], 12, v[94:95]
	v_or_b32_e32 v94, s60, v2
	v_lshl_add_u64 v[116:117], v[14:15], 0, v[132:133]
	v_lshlrev_b64 v[120:121], 12, v[94:95]
	global_load_dword v132, v[116:117], off nt
	v_lshl_add_u64 v[116:117], v[14:15], 0, v[120:121]
	global_load_dword v120, v[116:117], off nt
	s_add_i32 s43, s43, 16
	s_add_i32 s3, s3, 16
	s_add_i32 s44, s44, -16
	s_cmp_lg_u32 s44, 0
	v_mad_u64_u32 v[16:17], s[46:47], v16, s85, v[6:7]
	v_mad_u64_u32 v[22:23], s[46:47], v22, s85, v[6:7]
	v_mad_u64_u32 v[24:25], s[46:47], v24, s85, v[6:7]
	v_mad_u64_u32 v[26:27], s[46:47], v26, s85, v[6:7]
	v_mad_u64_u32 v[28:29], s[46:47], v28, s85, v[6:7]
	v_mad_u64_u32 v[30:31], s[46:47], v30, s85, v[6:7]
	v_mad_u64_u32 v[32:33], s[46:47], v32, s85, v[6:7]
	v_mad_u64_u32 v[34:35], s[46:47], v34, s85, v[6:7]
	v_mad_u64_u32 v[36:37], s[46:47], v0, s85, v[6:7]
	s_waitcnt vmcnt(31)
	ds_write_b32 v42, v5
	s_waitcnt vmcnt(30)
	ds_write_b32 v16, v21
	s_waitcnt vmcnt(29)
	ds_write_b32 v48, v39
	s_waitcnt vmcnt(28)
	ds_write_b32 v22, v43
	s_waitcnt vmcnt(21)
	ds_write_b32 v64, v51
	ds_write_b32 v24, v45
	s_waitcnt vmcnt(20)
	ds_write_b32 v44, v59
	ds_write_b32 v26, v49
	s_waitcnt vmcnt(19)
	ds_write_b32 v50, v47
	ds_write_b32 v28, v62
	s_waitcnt vmcnt(18)
	ds_write_b32 v46, v55
	ds_write_b32 v30, v56
	s_waitcnt vmcnt(17)
	ds_write_b32 v54, v52
	ds_write_b32 v32, v57
	s_waitcnt vmcnt(16)
	ds_write_b32 v36, v40
	ds_write_b32 v34, v58
	v_mad_u64_u32 v[98:99], s[46:47], v98, s85, v[6:7]
	v_mad_u64_u32 v[102:103], s[46:47], v102, s85, v[6:7]
	v_mad_u64_u32 v[104:105], s[46:47], v104, s85, v[6:7]
	v_mad_u64_u32 v[106:107], s[46:47], v106, s85, v[6:7]
	v_mad_u64_u32 v[108:109], s[46:47], v108, s85, v[6:7]
	v_mad_u64_u32 v[110:111], s[46:47], v110, s85, v[6:7]
	v_mad_u64_u32 v[112:113], s[46:47], v112, s85, v[6:7]
	v_mad_u64_u32 v[114:115], s[46:47], v114, s85, v[6:7]
	v_mad_u64_u32 v[116:117], s[46:47], v94, s85, v[6:7]
	s_waitcnt vmcnt(15)
	ds_write_b32 v122, v97
	s_waitcnt vmcnt(14)
	ds_write_b32 v98, v101
	s_waitcnt vmcnt(13)
	ds_write_b32 v128, v119
	s_waitcnt vmcnt(12)
	ds_write_b32 v102, v123
	s_waitcnt vmcnt(5)
	ds_write_b32 v156, v131
	ds_write_b32 v104, v125
	s_waitcnt vmcnt(4)
	ds_write_b32 v124, v151
	ds_write_b32 v106, v129
	s_waitcnt vmcnt(3)
	ds_write_b32 v130, v127
	ds_write_b32 v108, v154
	s_waitcnt vmcnt(2)
	ds_write_b32 v126, v135
	ds_write_b32 v110, v136
	s_waitcnt vmcnt(1)
	ds_write_b32 v134, v132
	ds_write_b32 v112, v137
	s_waitcnt vmcnt(0)
	ds_write_b32 v116, v120
	ds_write_b32 v114, v150
	s_waitcnt lgkmcnt(0)
	ds_read2_b32 v[14:15], v9 offset1:33
	s_waitcnt lgkmcnt(0)
	v_cvt_pk_bf16_f32 v14, v14, v15
	ds_read2_b32 v[16:17], v9 offset0:66 offset1:99
	s_lshl_b64 s[44:45], s[0:1], 17
	v_or_b32_e32 v0, s2, v7
	s_waitcnt lgkmcnt(0)
	v_cvt_pk_bf16_f32 v15, v16, v17
	ds_read2_b32 v[16:17], v9 offset0:132 offset1:165
	v_lshl_add_u64 v[24:25], v[10:11], 0, s[44:45]
	v_lshlrev_b32_e32 v0, 7, v0
	s_waitcnt lgkmcnt(0)
	v_cvt_pk_bf16_f32 v16, v16, v17
	ds_read2_b32 v[22:23], v9 offset0:198 offset1:231
	s_waitcnt lgkmcnt(0)
	v_cvt_pk_bf16_f32 v17, v22, v23
	v_lshl_add_u64 v[26:27], v[24:25], 0, v[0:1]
	ds_read2_b32 v[22:23], v9 offset0:8 offset1:41
	global_store_dwordx4 v[26:27], v[14:17], off sc1
	v_or_b32_e32 v0, s2, v18
	v_lshlrev_b32_e32 v0, 7, v0
	s_waitcnt lgkmcnt(0)
	v_cvt_pk_bf16_f32 v14, v22, v23
	ds_read2_b32 v[16:17], v9 offset0:74 offset1:107
	s_waitcnt lgkmcnt(0)
	v_cvt_pk_bf16_f32 v15, v16, v17
	ds_read2_b32 v[16:17], v9 offset0:140 offset1:173
	s_waitcnt lgkmcnt(0)
	v_cvt_pk_bf16_f32 v16, v16, v17
	ds_read2_b32 v[22:23], v9 offset0:206 offset1:239
	s_waitcnt lgkmcnt(0)
	v_cvt_pk_bf16_f32 v17, v22, v23
	v_lshl_add_u64 v[26:27], v[24:25], 0, v[0:1]
	ds_read2_b32 v[22:23], v9 offset0:16 offset1:49
	global_store_dwordx4 v[26:27], v[14:17], off sc1
	v_or_b32_e32 v0, s2, v19
	v_lshlrev_b32_e32 v0, 7, v0
	s_waitcnt lgkmcnt(0)
	v_cvt_pk_bf16_f32 v14, v22, v23
	ds_read2_b32 v[16:17], v9 offset0:82 offset1:115
	s_waitcnt lgkmcnt(0)
	v_cvt_pk_bf16_f32 v15, v16, v17
	ds_read2_b32 v[16:17], v9 offset0:148 offset1:181
	s_waitcnt lgkmcnt(0)
	v_cvt_pk_bf16_f32 v16, v16, v17
	ds_read2_b32 v[22:23], v9 offset0:214 offset1:247
	s_waitcnt lgkmcnt(0)
	v_cvt_pk_bf16_f32 v17, v22, v23
	v_lshl_add_u64 v[26:27], v[24:25], 0, v[0:1]
	ds_read2_b32 v[22:23], v9 offset0:24 offset1:57
	global_store_dwordx4 v[26:27], v[14:17], off sc1
	v_or_b32_e32 v0, s2, v20
	v_lshlrev_b32_e32 v0, 7, v0
	s_waitcnt lgkmcnt(0)
	v_cvt_pk_bf16_f32 v14, v22, v23
	ds_read2_b32 v[16:17], v9 offset0:90 offset1:123
	s_waitcnt lgkmcnt(0)
	v_cvt_pk_bf16_f32 v15, v16, v17
	ds_read2_b32 v[16:17], v9 offset0:156 offset1:189
	s_waitcnt lgkmcnt(0)
	v_cvt_pk_bf16_f32 v16, v16, v17
	ds_read2_b32 v[22:23], v9 offset0:222 offset1:255
	s_waitcnt lgkmcnt(0)
	v_cvt_pk_bf16_f32 v17, v22, v23
	v_lshl_add_u64 v[22:23], v[24:25], 0, v[0:1]
	global_store_dwordx4 v[22:23], v[14:17], off sc1
	s_waitcnt lgkmcnt(0)
	v_readlane_b32 s70, v253, 44
	s_mov_b64 s[2:3], 0
	v_readlane_b32 s71, v253, 45
	s_mov_b32 s48, 0x3a000000

; #define LDS_WAIT() asm volatile("s_waitcnt lgkmcnt(0)" ::: "memory")
;     ...
; #pragma unroll 8
;     for (int i = 0; i < 32; ++i) { const int kk = 2 * i + (lane >> 5); scr[kk * 33 + (lane & 31)] = W[(size_t)(k0 + kk) * N + n0 + (lane & 31)]; }
;     LDS_WAIT(); asm volatile("" ::: "memory");
.LBB0_479:
	s_lshl_b32 s41, s3, 1
	s_lshl_b32 s43, s38, 1
	v_or_b32_e32 v0, s43, v2
	s_add_i32 s46, s41, 4
	s_add_i32 s47, s43, 4
	v_mov_b32_e32 v23, v1
	s_add_i32 s48, s41, 8
	s_add_i32 s49, s43, 8
	s_add_i32 s54, s41, 20
	s_add_i32 s56, s41, 24
	v_lshlrev_b64 v[40:41], 12, v[0:1]
	v_mad_u64_u32 v[42:43], s[44:45], v0, s85, v[6:7]
	v_or_b32_e32 v22, s46, v3
	v_or_b32_e32 v0, s47, v2
	v_mov_b32_e32 v17, v1
	v_mov_b32_e32 v25, v1
	v_mov_b32_e32 v31, v1
	v_mov_b32_e32 v33, v1
	v_or_b32_e32 v16, s41, v3
	s_add_i32 s50, s41, 12
	s_add_i32 s51, s43, 12
	s_add_i32 s52, s41, 16
	s_add_i32 s41, s41, 28
	v_or_b32_e32 v24, s48, v3
	v_or_b32_e32 v30, s54, v3
	v_or_b32_e32 v32, s56, v3
	v_lshlrev_b64 v[44:45], 12, v[22:23]
	v_lshlrev_b64 v[46:47], 12, v[0:1]
	v_mad_u64_u32 v[48:49], s[44:45], v0, s85, v[6:7]
	v_or_b32_e32 v0, s49, v2
	v_mov_b32_e32 v27, v1
	v_mov_b32_e32 v29, v1
	v_mov_b32_e32 v35, v1
	s_add_i32 s53, s43, 16
	v_lshlrev_b64 v[36:37], 12, v[16:17]
	v_or_b32_e32 v26, s50, v3
	v_or_b32_e32 v28, s52, v3
	v_or_b32_e32 v34, s41, v3
	v_lshl_add_u64 v[40:41], v[14:15], 0, v[40:41]
	v_lshlrev_b64 v[50:51], 12, v[24:25]
	v_lshlrev_b64 v[56:57], 12, v[30:31]
	v_lshlrev_b64 v[58:59], 12, v[32:33]
	v_lshl_add_u64 v[44:45], v[14:15], 0, v[44:45]
	v_lshlrev_b64 v[62:63], 12, v[0:1]
	v_mad_u64_u32 v[64:65], s[44:45], v0, s85, v[6:7]
	v_or_b32_e32 v0, s51, v2
	s_add_i32 s55, s43, 20
	v_lshl_add_u64 v[36:37], v[14:15], 0, v[36:37]
	v_lshlrev_b64 v[52:53], 12, v[26:27]
	v_lshlrev_b64 v[54:55], 12, v[28:29]
	v_lshlrev_b64 v[60:61], 12, v[34:35]
	v_lshl_add_u64 v[46:47], v[14:15], 0, v[46:47]
	v_lshl_add_u64 v[50:51], v[14:15], 0, v[50:51]
	v_lshl_add_u64 v[56:57], v[14:15], 0, v[56:57]
	v_lshl_add_u64 v[58:59], v[14:15], 0, v[58:59]
	global_load_dword v5, v[40:41], off nt
	global_load_dword v21, v[36:37], off nt
	global_load_dword v39, v[46:47], off nt
	global_load_dword v43, v[44:45], off nt
	v_lshlrev_b64 v[40:41], 12, v[0:1]
	v_mad_u64_u32 v[44:45], s[44:45], v0, s85, v[6:7]
	v_or_b32_e32 v0, s53, v2
	s_add_i32 s57, s43, 24
	v_lshl_add_u64 v[52:53], v[14:15], 0, v[52:53]
	v_lshl_add_u64 v[54:55], v[14:15], 0, v[54:55]
	v_lshl_add_u64 v[60:61], v[14:15], 0, v[60:61]
	v_lshl_add_u64 v[36:37], v[14:15], 0, v[62:63]
	global_load_dword v45, v[50:51], off nt
	global_load_dword v49, v[52:53], off nt
	global_load_dword v62, v[54:55], off nt
	s_nop 0
	global_load_dword v56, v[56:57], off nt
	s_nop 0
	global_load_dword v57, v[58:59], off nt
	s_nop 0
	global_load_dword v58, v[60:61], off nt
	v_lshl_add_u64 v[40:41], v[14:15], 0, v[40:41]
	v_lshlrev_b64 v[46:47], 12, v[0:1]
	v_mad_u64_u32 v[50:51], s[44:45], v0, s85, v[6:7]
	v_or_b32_e32 v0, s55, v2
	global_load_dword v51, v[36:37], off nt
	global_load_dword v59, v[40:41], off nt
	v_lshl_add_u64 v[36:37], v[14:15], 0, v[46:47]
	v_lshlrev_b64 v[40:41], 12, v[0:1]
	v_mad_u64_u32 v[46:47], s[44:45], v0, s85, v[6:7]
	v_or_b32_e32 v0, s57, v2
	v_mad_u64_u32 v[54:55], s[44:45], v0, s85, v[6:7]
	v_lshl_add_u64 v[40:41], v[14:15], 0, v[40:41]
	global_load_dword v47, v[36:37], off nt
	global_load_dword v55, v[40:41], off nt
	s_add_i32 s43, s43, 28
	v_lshlrev_b64 v[52:53], 12, v[0:1]
	v_or_b32_e32 v0, s43, v2
	v_lshl_add_u64 v[36:37], v[14:15], 0, v[52:53]
	v_lshlrev_b64 v[40:41], 12, v[0:1]
	global_load_dword v52, v[36:37], off nt
	v_lshl_add_u64 v[36:37], v[14:15], 0, v[40:41]
	global_load_dword v40, v[36:37], off nt
	s_add_i32 s38, s38, 16
	s_add_i32 s3, s3, 16
	s_add_i32 s39, s39, -16
	s_cmp_lg_u32 s39, 0
	v_mov_b32_e32 v95, 0
	s_lshl_b32 s41, s3, 1
	s_lshl_b32 s43, s38, 1
	v_or_b32_e32 v94, s43, v2
	s_add_i32 s46, s41, 4
	s_add_i32 s47, s43, 4
	v_mov_b32_e32 v103, v95
	s_add_i32 s48, s41, 8
	s_add_i32 s49, s43, 8
	s_add_i32 s54, s41, 20
	s_add_i32 s56, s41, 24
	v_lshlrev_b64 v[120:121], 12, v[94:95]
	v_mad_u64_u32 v[122:123], s[44:45], v94, s85, v[6:7]
	v_or_b32_e32 v102, s46, v3
	v_or_b32_e32 v94, s47, v2
	v_mov_b32_e32 v99, v95
	v_mov_b32_e32 v105, v95
	v_mov_b32_e32 v111, v95
	v_mov_b32_e32 v113, v95
	v_or_b32_e32 v98, s41, v3
	s_add_i32 s50, s41, 12
	s_add_i32 s51, s43, 12
	s_add_i32 s52, s41, 16
	s_add_i32 s41, s41, 28
	v_or_b32_e32 v104, s48, v3
	v_or_b32_e32 v110, s54, v3
	v_or_b32_e32 v112, s56, v3
	v_lshlrev_b64 v[124:125], 12, v[102:103]
	v_lshlrev_b64 v[126:127], 12, v[94:95]
	v_mad_u64_u32 v[128:129], s[44:45], v94, s85, v[6:7]
	v_or_b32_e32 v94, s49, v2
	v_mov_b32_e32 v107, v95
	v_mov_b32_e32 v109, v95
	v_mov_b32_e32 v115, v95
	s_add_i32 s53, s43, 16
	v_lshlrev_b64 v[116:117], 12, v[98:99]
	v_or_b32_e32 v106, s50, v3
	v_or_b32_e32 v108, s52, v3
	v_or_b32_e32 v114, s41, v3
	v_lshl_add_u64 v[120:121], v[14:15], 0, v[120:121]
	v_lshlrev_b64 v[130:131], 12, v[104:105]
	v_lshlrev_b64 v[136:137], 12, v[110:111]
	v_lshlrev_b64 v[150:151], 12, v[112:113]
	v_lshl_add_u64 v[124:125], v[14:15], 0, v[124:125]
	v_lshlrev_b64 v[154:155], 12, v[94:95]
	v_mad_u64_u32 v[156:157], s[44:45], v94, s85, v[6:7]
	v_or_b32_e32 v94, s51, v2
	s_add_i32 s55, s43, 20
	v_lshl_add_u64 v[116:117], v[14:15], 0, v[116:117]
	v_lshlrev_b64 v[132:133], 12, v[106:107]
	v_lshlrev_b64 v[134:135], 12, v[108:109]
	v_lshlrev_b64 v[152:153], 12, v[114:115]
	v_lshl_add_u64 v[126:127], v[14:15], 0, v[126:127]
	v_lshl_add_u64 v[130:131], v[14:15], 0, v[130:131]
	v_lshl_add_u64 v[136:137], v[14:15], 0, v[136:137]
	v_lshl_add_u64 v[150:151], v[14:15], 0, v[150:151]
	global_load_dword v97, v[120:121], off nt
	global_load_dword v101, v[116:117], off nt
	global_load_dword v119, v[126:127], off nt
	global_load_dword v123, v[124:125], off nt
	v_lshlrev_b64 v[120:121], 12, v[94:95]
	v_mad_u64_u32 v[124:125], s[44:45], v94, s85, v[6:7]
	v_or_b32_e32 v94, s53, v2
; __device__ __forceinline__ unsigned cvt_pk_bf16(float lo, float hi) { unsigned r; asm volatile("v_cvt_pk_bf16_f32 %0, %1, %2" : "=v"(r) : "v"(lo), "v"(hi)); return r; }
; #define LAS __attribute__((address_space(3)))
; #define LDS_WAIT() asm volatile("s_waitcnt lgkmcnt(0)" ::: "memory")
;     ...
;     for (int i = 0; i < 32; ++i) { const int kk = 2 * i + (lane >> 5); scr[kk * 33 + (lane & 31)] = W[(size_t)(k0 + kk) * N + n0 + (lane & 31)]; }
;     LDS_WAIT(); asm volatile("" ::: "memory");
;     const int c = lane & 7;
; #pragma unroll
;     for (int j = 0; j < 4; ++j) { const int n = (lane >> 3) + 8 * j; const LAS float* s = scr + (8 * c) * 33 + n;
;         u32x4 o; o.x = cvt_pk_bf16(s[0 * 33], s[1 * 33]); o.y = cvt_pk_bf16(s[2 * 33], s[3 * 33]); o.z = cvt_pk_bf16(s[4 * 33], s[5 * 33]); o.w = cvt_pk_bf16(s[6 * 33], s[7 * 33]);
;         *(u32x4*)(WT + (size_t)(dn0 + n) * ldo + koff + k0 + 8 * c) = o; }
;     LDS_WAIT(); asm volatile("" ::: "memory");
	s_add_i32 s57, s43, 24
	v_lshl_add_u64 v[132:133], v[14:15], 0, v[132:133]
	v_lshl_add_u64 v[134:135], v[14:15], 0, v[134:135]
	v_lshl_add_u64 v[152:153], v[14:15], 0, v[152:153]
	v_lshl_add_u64 v[116:117], v[14:15], 0, v[154:155]
	global_load_dword v125, v[130:131], off nt
	global_load_dword v129, v[132:133], off nt
	global_load_dword v154, v[134:135], off nt
	s_nop 0
	global_load_dword v136, v[136:137], off nt
	s_nop 0
	global_load_dword v137, v[150:151], off nt
	s_nop 0
	global_load_dword v150, v[152:153], off nt
	v_lshl_add_u64 v[120:121], v[14:15], 0, v[120:121]
	v_lshlrev_b64 v[126:127], 12, v[94:95]
	v_mad_u64_u32 v[130:131], s[44:45], v94, s85, v[6:7]
	v_or_b32_e32 v94, s55, v2
	global_load_dword v131, v[116:117], off nt
	global_load_dword v151, v[120:121], off nt
	v_lshl_add_u64 v[116:117], v[14:15], 0, v[126:127]
	v_lshlrev_b64 v[120:121], 12, v[94:95]
	v_mad_u64_u32 v[126:127], s[44:45], v94, s85, v[6:7]
	v_or_b32_e32 v94, s57, v2
	v_mad_u64_u32 v[134:135], s[44:45], v94, s85, v[6:7]
	v_lshl_add_u64 v[120:121], v[14:15], 0, v[120:121]
	global_load_dword v127, v[116:117], off nt
	global_load_dword v135, v[120:121], off nt
	s_add_i32 s43, s43, 28
	v_lshlrev_b64 v[132:133], 12, v[94:95]
	v_or_b32_e32 v94, s43, v2
	v_lshl_add_u64 v[116:117], v[14:15], 0, v[132:133]
	v_lshlrev_b64 v[120:121], 12, v[94:95]
	global_load_dword v132, v[116:117], off nt
	v_lshl_add_u64 v[116:117], v[14:15], 0, v[120:121]
	global_load_dword v120, v[116:117], off nt
	s_add_i32 s38, s38, 16
	s_add_i32 s3, s3, 16
	s_add_i32 s39, s39, -16
	s_cmp_lg_u32 s39, 0
	v_mad_u64_u32 v[16:17], s[44:45], v16, s85, v[6:7]
	v_mad_u64_u32 v[22:23], s[44:45], v22, s85, v[6:7]
	v_mad_u64_u32 v[24:25], s[44:45], v24, s85, v[6:7]
	v_mad_u64_u32 v[26:27], s[44:45], v26, s85, v[6:7]
	v_mad_u64_u32 v[28:29], s[44:45], v28, s85, v[6:7]
	v_mad_u64_u32 v[30:31], s[44:45], v30, s85, v[6:7]
	v_mad_u64_u32 v[32:33], s[44:45], v32, s85, v[6:7]
	v_mad_u64_u32 v[34:35], s[44:45], v34, s85, v[6:7]
	v_mad_u64_u32 v[36:37], s[44:45], v0, s85, v[6:7]
	s_waitcnt vmcnt(31)
	ds_write_b32 v42, v5
	s_waitcnt vmcnt(30)
	ds_write_b32 v16, v21
	s_waitcnt vmcnt(29)
	ds_write_b32 v48, v39
	s_waitcnt vmcnt(28)
	ds_write_b32 v22, v43
	s_waitcnt vmcnt(21)
	ds_write_b32 v64, v51
	ds_write_b32 v24, v45
	s_waitcnt vmcnt(20)
	ds_write_b32 v44, v59
	ds_write_b32 v26, v49
	s_waitcnt vmcnt(19)
	ds_write_b32 v50, v47
	ds_write_b32 v28, v62
	s_waitcnt vmcnt(18)
	ds_write_b32 v46, v55
	ds_write_b32 v30, v56
	s_waitcnt vmcnt(17)
	ds_write_b32 v54, v52
	ds_write_b32 v32, v57
	s_waitcnt vmcnt(16)
	ds_write_b32 v36, v40
	ds_write_b32 v34, v58
	v_mad_u64_u32 v[98:99], s[44:45], v98, s85, v[6:7]
	v_mad_u64_u32 v[102:103], s[44:45], v102, s85, v[6:7]
	v_mad_u64_u32 v[104:105], s[44:45], v104, s85, v[6:7]
	v_mad_u64_u32 v[106:107], s[44:45], v106, s85, v[6:7]
	v_mad_u64_u32 v[108:109], s[44:45], v108, s85, v[6:7]
	v_mad_u64_u32 v[110:111], s[44:45], v110, s85, v[6:7]
	v_mad_u64_u32 v[112:113], s[44:45], v112, s85, v[6:7]
	v_mad_u64_u32 v[114:115], s[44:45], v114, s85, v[6:7]
	v_mad_u64_u32 v[116:117], s[44:45], v94, s85, v[6:7]
	s_waitcnt vmcnt(15)
	ds_write_b32 v122, v97
	s_waitcnt vmcnt(14)
	ds_write_b32 v98, v101
	s_waitcnt vmcnt(13)
	ds_write_b32 v128, v119
	s_waitcnt vmcnt(12)
	ds_write_b32 v102, v123
	s_waitcnt vmcnt(5)
	ds_write_b32 v156, v131
	ds_write_b32 v104, v125
	s_waitcnt vmcnt(4)
	ds_write_b32 v124, v151
	ds_write_b32 v106, v129
	s_waitcnt vmcnt(3)
	ds_write_b32 v130, v127
	ds_write_b32 v108, v154
	s_waitcnt vmcnt(2)
	ds_write_b32 v126, v135
	ds_write_b32 v110, v136
	s_waitcnt vmcnt(1)
	ds_write_b32 v134, v132
	ds_write_b32 v112, v137
	s_waitcnt vmcnt(0)
	ds_write_b32 v116, v120
	ds_write_b32 v114, v150
	s_waitcnt lgkmcnt(0)
	ds_read2_b32 v[14:15], v9 offset1:33
	s_waitcnt lgkmcnt(0)
	v_cvt_pk_bf16_f32 v14, v14, v15
	ds_read2_b32 v[16:17], v9 offset0:66 offset1:99
	s_lshl_b64 s[38:39], s[0:1], 17
	v_or_b32_e32 v0, s2, v7
	s_waitcnt lgkmcnt(0)
	v_cvt_pk_bf16_f32 v15, v16, v17
	ds_read2_b32 v[16:17], v9 offset0:132 offset1:165
	v_lshl_add_u64 v[24:25], v[12:13], 0, s[38:39]
	v_lshlrev_b32_e32 v0, 7, v0
	s_waitcnt lgkmcnt(0)
	v_cvt_pk_bf16_f32 v16, v16, v17
	ds_read2_b32 v[22:23], v9 offset0:198 offset1:231
	s_waitcnt lgkmcnt(0)
	v_cvt_pk_bf16_f32 v17, v22, v23
	v_lshl_add_u64 v[26:27], v[24:25], 0, v[0:1]
	ds_read2_b32 v[22:23], v9 offset0:8 offset1:41
	global_store_dwordx4 v[26:27], v[14:17], off sc1
	v_or_b32_e32 v0, s2, v18
	v_lshlrev_b32_e32 v0, 7, v0
	s_waitcnt lgkmcnt(0)
	v_cvt_pk_bf16_f32 v14, v22, v23
	ds_read2_b32 v[16:17], v9 offset0:74 offset1:107
	s_waitcnt lgkmcnt(0)
	v_cvt_pk_bf16_f32 v15, v16, v17
	ds_read2_b32 v[16:17], v9 offset0:140 offset1:173
	s_waitcnt lgkmcnt(0)
	v_cvt_pk_bf16_f32 v16, v16, v17
	ds_read2_b32 v[22:23], v9 offset0:206 offset1:239
	s_waitcnt lgkmcnt(0)
	v_cvt_pk_bf16_f32 v17, v22, v23
	v_lshl_add_u64 v[26:27], v[24:25], 0, v[0:1]
	ds_read2_b32 v[22:23], v9 offset0:16 offset1:49
	global_store_dwordx4 v[26:27], v[14:17], off sc1
	v_or_b32_e32 v0, s2, v19
	v_lshlrev_b32_e32 v0, 7, v0
	s_waitcnt lgkmcnt(0)
	v_cvt_pk_bf16_f32 v14, v22, v23
	ds_read2_b32 v[16:17], v9 offset0:82 offset1:115
	s_waitcnt lgkmcnt(0)
	v_cvt_pk_bf16_f32 v15, v16, v17
	ds_read2_b32 v[16:17], v9 offset0:148 offset1:181
	s_waitcnt lgkmcnt(0)
	v_cvt_pk_bf16_f32 v16, v16, v17
	ds_read2_b32 v[22:23], v9 offset0:214 offset1:247
	s_waitcnt lgkmcnt(0)
	v_cvt_pk_bf16_f32 v17, v22, v23
	v_lshl_add_u64 v[26:27], v[24:25], 0, v[0:1]
	ds_read2_b32 v[22:23], v9 offset0:24 offset1:57
	global_store_dwordx4 v[26:27], v[14:17], off sc1
	v_or_b32_e32 v0, s2, v20
	v_lshlrev_b32_e32 v0, 7, v0
	s_waitcnt lgkmcnt(0)
	v_cvt_pk_bf16_f32 v14, v22, v23
	ds_read2_b32 v[16:17], v9 offset0:90 offset1:123
	s_waitcnt lgkmcnt(0)
	v_cvt_pk_bf16_f32 v15, v16, v17
	ds_read2_b32 v[16:17], v9 offset0:156 offset1:189
	s_waitcnt lgkmcnt(0)
	v_cvt_pk_bf16_f32 v16, v16, v17
	ds_read2_b32 v[22:23], v9 offset0:222 offset1:255
	s_waitcnt lgkmcnt(0)
	v_cvt_pk_bf16_f32 v17, v22, v23
	v_lshl_add_u64 v[22:23], v[24:25], 0, v[0:1]
	global_store_dwordx4 v[22:23], v[14:17], off sc1
	s_waitcnt lgkmcnt(0)
	s_mov_b32 s48, 0x3a000000

; #define LDS_WAIT() asm volatile("s_waitcnt lgkmcnt(0)" ::: "memory")
;     ...
; #pragma unroll 8
;     for (int i = 0; i < 32; ++i) { const int kk = 2 * i + (lane >> 5); scr[kk * 33 + (lane & 31)] = W[(size_t)(k0 + kk) * N + n0 + (lane & 31)]; }
;     LDS_WAIT(); asm volatile("" ::: "memory");
.LBB0_484:
	s_lshl_b32 s46, s43, 1
	s_lshl_b32 s45, s41, 1
	v_or_b32_e32 v0, s46, v16
	s_add_i32 s49, s46, 4
	s_add_i32 s48, s45, 4
	s_add_i32 s50, s45, 8
	s_add_i32 s51, s46, 8
	v_lshlrev_b64 v[40:41], 13, v[0:1]
	v_or_b32_e32 v0, s49, v16
	v_mov_b32_e32 v23, v1
	v_mov_b32_e32 v25, v1
	v_mov_b32_e32 v27, v1
	v_or_b32_e32 v22, s45, v5
	s_add_i32 s52, s45, 12
	s_add_i32 s53, s46, 12
	s_add_i32 s54, s45, 16
	s_add_i32 s56, s45, 20
	s_add_i32 s58, s45, 24
	s_add_i32 s60, s45, 28
	v_or_b32_e32 v24, s48, v5
	v_or_b32_e32 v26, s50, v5
	v_lshlrev_b64 v[42:43], 13, v[0:1]
	v_or_b32_e32 v0, s51, v16
	v_mov_b32_e32 v29, v1
	v_mov_b32_e32 v31, v1
	v_mov_b32_e32 v33, v1
	v_mov_b32_e32 v35, v1
	v_mov_b32_e32 v37, v1
	s_add_i32 s55, s46, 16
	v_lshlrev_b64 v[22:23], 13, v[22:23]
	v_or_b32_e32 v28, s52, v5
	v_or_b32_e32 v30, s54, v5
	v_or_b32_e32 v32, s56, v5
	v_or_b32_e32 v34, s58, v5
	v_or_b32_e32 v36, s60, v5
	v_lshl_add_u64 v[40:41], v[14:15], 0, v[40:41]
	v_lshlrev_b64 v[24:25], 13, v[24:25]
	v_lshlrev_b64 v[26:27], 13, v[26:27]
	v_lshlrev_b64 v[44:45], 13, v[0:1]
	v_or_b32_e32 v0, s53, v16
	s_add_i32 s57, s46, 20
	v_lshl_add_u64 v[22:23], v[14:15], 0, v[22:23]
	v_lshlrev_b64 v[28:29], 13, v[28:29]
	v_lshlrev_b64 v[30:31], 13, v[30:31]
	v_lshlrev_b64 v[32:33], 13, v[32:33]
	v_lshlrev_b64 v[34:35], 13, v[34:35]
	v_lshlrev_b64 v[36:37], 13, v[36:37]
	v_lshl_add_u64 v[42:43], v[14:15], 0, v[42:43]
	v_lshl_add_u64 v[24:25], v[14:15], 0, v[24:25]
	v_lshl_add_u64 v[26:27], v[14:15], 0, v[26:27]
	global_load_dword v17, v[40:41], off nt
	global_load_dword v21, v[22:23], off nt
	v_lshlrev_b64 v[40:41], 13, v[0:1]
	v_or_b32_e32 v0, s55, v16
	s_add_i32 s59, s46, 24
	v_lshl_add_u64 v[28:29], v[14:15], 0, v[28:29]
	v_lshl_add_u64 v[30:31], v[14:15], 0, v[30:31]
	v_lshl_add_u64 v[32:33], v[14:15], 0, v[32:33]
	v_lshl_add_u64 v[34:35], v[14:15], 0, v[34:35]
	v_lshl_add_u64 v[36:37], v[14:15], 0, v[36:37]
	global_load_dword v39, v[42:43], off nt
	global_load_dword v56, v[24:25], off nt
	global_load_dword v57, v[26:27], off nt
	global_load_dword v58, v[28:29], off nt
	global_load_dword v59, v[30:31], off nt
	global_load_dword v60, v[32:33], off nt
	global_load_dword v61, v[34:35], off nt
	global_load_dword v62, v[36:37], off nt
	v_lshl_add_u64 v[24:25], v[14:15], 0, v[40:41]
	v_lshlrev_b64 v[26:27], 13, v[0:1]
	v_or_b32_e32 v0, s57, v16
	s_add_i32 s61, s46, 28
	v_lshl_add_u64 v[22:23], v[14:15], 0, v[44:45]
	global_load_dword v63, v[24:25], off nt
	global_load_dword v64, v[22:23], off nt
	v_lshlrev_b64 v[24:25], 13, v[0:1]
	v_or_b32_e32 v0, s59, v16
	v_lshl_add_u64 v[22:23], v[14:15], 0, v[26:27]
	v_lshlrev_b64 v[26:27], 13, v[0:1]
	v_or_b32_e32 v0, s61, v16
	v_lshlrev_b64 v[28:29], 13, v[0:1]
	v_lshl_add_u64 v[28:29], v[14:15], 0, v[28:29]
	v_lshl_add_u64 v[24:25], v[14:15], 0, v[24:25]
	v_lshl_add_u64 v[26:27], v[14:15], 0, v[26:27]
	global_load_dword v0, v[28:29], off nt
	global_load_dword v65, v[26:27], off nt
	global_load_dword v66, v[24:25], off nt
	global_load_dword v67, v[22:23], off nt
	v_or_b32_e32 v214, s45, v3
	v_or_b32_e32 v215, s46, v2
	v_or_b32_e32 v216, s48, v3
	v_or_b32_e32 v217, s49, v2
	v_or_b32_e32 v218, s50, v3
	v_or_b32_e32 v219, s51, v2
	v_or_b32_e32 v220, s52, v3
	v_or_b32_e32 v221, s53, v2
	v_or_b32_e32 v222, s54, v3
	v_or_b32_e32 v223, s55, v2
	v_or_b32_e32 v224, s56, v3
	v_or_b32_e32 v225, s57, v2
	v_or_b32_e32 v226, s58, v3
	v_or_b32_e32 v227, s59, v2
	v_or_b32_e32 v228, s60, v3
	v_or_b32_e32 v229, s61, v2
	s_add_i32 s43, s43, 16
	s_add_i32 s41, s41, 16
	s_add_i32 s44, s44, -16
	s_cmp_lg_u32 s44, 0
	v_mov_b32_e32 v95, 0
	s_lshl_b32 s46, s43, 1
	s_lshl_b32 s45, s41, 1
	v_or_b32_e32 v94, s46, v16
	s_add_i32 s49, s46, 4
	s_add_i32 s48, s45, 4
	s_add_i32 s50, s45, 8
	s_add_i32 s51, s46, 8
	v_lshlrev_b64 v[118:119], 13, v[94:95]
	v_or_b32_e32 v94, s49, v16
	v_mov_b32_e32 v101, v95
	v_mov_b32_e32 v103, v95
	v_mov_b32_e32 v105, v95
	v_or_b32_e32 v100, s45, v5
	s_add_i32 s52, s45, 12
	s_add_i32 s53, s46, 12
	s_add_i32 s54, s45, 16
	s_add_i32 s56, s45, 20
	s_add_i32 s58, s45, 24
	s_add_i32 s60, s45, 28
	v_or_b32_e32 v102, s48, v5
	v_or_b32_e32 v104, s50, v5
	v_lshlrev_b64 v[120:121], 13, v[94:95]
	v_or_b32_e32 v94, s51, v16
	v_mov_b32_e32 v107, v95
	v_mov_b32_e32 v109, v95
	v_mov_b32_e32 v111, v95
	v_mov_b32_e32 v113, v95
	v_mov_b32_e32 v115, v95
	s_add_i32 s55, s46, 16
	v_lshlrev_b64 v[100:101], 13, v[100:101]
	v_or_b32_e32 v106, s52, v5
	v_or_b32_e32 v108, s54, v5
	v_or_b32_e32 v110, s56, v5
	v_or_b32_e32 v112, s58, v5
	v_or_b32_e32 v114, s60, v5
	v_lshl_add_u64 v[118:119], v[14:15], 0, v[118:119]
	v_lshlrev_b64 v[102:103], 13, v[102:103]
	v_lshlrev_b64 v[104:105], 13, v[104:105]
	v_lshlrev_b64 v[122:123], 13, v[94:95]
	v_or_b32_e32 v94, s53, v16
	s_add_i32 s57, s46, 20
	v_lshl_add_u64 v[100:101], v[14:15], 0, v[100:101]
	v_lshlrev_b64 v[106:107], 13, v[106:107]
	v_lshlrev_b64 v[108:109], 13, v[108:109]
	v_lshlrev_b64 v[110:111], 13, v[110:111]
	v_lshlrev_b64 v[112:113], 13, v[112:113]
	v_lshlrev_b64 v[114:115], 13, v[114:115]
	v_lshl_add_u64 v[120:121], v[14:15], 0, v[120:121]
	v_lshl_add_u64 v[102:103], v[14:15], 0, v[102:103]
	v_lshl_add_u64 v[104:105], v[14:15], 0, v[104:105]
	global_load_dword v97, v[118:119], off nt
	global_load_dword v99, v[100:101], off nt
	v_lshlrev_b64 v[118:119], 13, v[94:95]
	v_or_b32_e32 v94, s55, v16
	s_add_i32 s59, s46, 24
	v_lshl_add_u64 v[106:107], v[14:15], 0, v[106:107]
	v_lshl_add_u64 v[108:109], v[14:15], 0, v[108:109]
	v_lshl_add_u64 v[110:111], v[14:15], 0, v[110:111]
	v_lshl_add_u64 v[112:113], v[14:15], 0, v[112:113]
	v_lshl_add_u64 v[114:115], v[14:15], 0, v[114:115]
	global_load_dword v117, v[120:121], off nt
; #define LDS_WAIT() asm volatile("s_waitcnt lgkmcnt(0)" ::: "memory")
;     ...
;     for (int i = 0; i < 32; ++i) { const int kk = 2 * i + (lane >> 5); scr[kk * 33 + (lane & 31)] = W[(size_t)(k0 + kk) * N + n0 + (lane & 31)]; }
;     LDS_WAIT(); asm volatile("" ::: "memory");
	global_load_dword v96, v[102:103], off nt
	global_load_dword v135, v[104:105], off nt
	global_load_dword v98, v[106:107], off nt
	global_load_dword v137, v[108:109], off nt
	global_load_dword v116, v[110:111], off nt
	global_load_dword v151, v[112:113], off nt
	global_load_dword v134, v[114:115], off nt
	v_lshl_add_u64 v[102:103], v[14:15], 0, v[118:119]
	v_lshlrev_b64 v[104:105], 13, v[94:95]
	v_or_b32_e32 v94, s57, v16
	s_add_i32 s61, s46, 28
	v_lshl_add_u64 v[100:101], v[14:15], 0, v[122:123]
	global_load_dword v153, v[102:103], off nt
	global_load_dword v136, v[100:101], off nt
	v_lshlrev_b64 v[102:103], 13, v[94:95]
	v_or_b32_e32 v94, s59, v16
	v_lshl_add_u64 v[100:101], v[14:15], 0, v[104:105]
	v_lshlrev_b64 v[104:105], 13, v[94:95]
	v_or_b32_e32 v94, s61, v16
	v_lshlrev_b64 v[106:107], 13, v[94:95]
	v_lshl_add_u64 v[106:107], v[14:15], 0, v[106:107]
	v_lshl_add_u64 v[102:103], v[14:15], 0, v[102:103]
	v_lshl_add_u64 v[104:105], v[14:15], 0, v[104:105]
	global_load_dword v94, v[106:107], off nt
	global_load_dword v155, v[104:105], off nt
	global_load_dword v138, v[102:103], off nt
	global_load_dword v157, v[100:101], off nt
	v_or_b32_e32 v150, s45, v3
	v_or_b32_e32 v159, s46, v2
	v_or_b32_e32 v152, s48, v3
	v_or_b32_e32 v161, s49, v2
	v_or_b32_e32 v154, s50, v3
	v_or_b32_e32 v163, s51, v2
	v_or_b32_e32 v156, s52, v3
	v_or_b32_e32 v165, s53, v2
	v_or_b32_e32 v158, s54, v3
	v_or_b32_e32 v167, s55, v2
	v_or_b32_e32 v160, s56, v3
	v_or_b32_e32 v169, s57, v2
	v_or_b32_e32 v162, s58, v3
	v_or_b32_e32 v183, s59, v2
	v_or_b32_e32 v164, s60, v3
	v_or_b32_e32 v185, s61, v2
	s_add_i32 s43, s43, 16
	s_add_i32 s41, s41, 16
	s_add_i32 s44, s44, -16
	s_cmp_lg_u32 s44, 0
	v_mad_u64_u32 v[22:23], s[46:47], v215, s85, v[6:7]
	v_mad_u64_u32 v[24:25], s[46:47], v214, s85, v[6:7]
	v_mad_u64_u32 v[26:27], s[46:47], v217, s85, v[6:7]
	v_mad_u64_u32 v[28:29], s[46:47], v216, s85, v[6:7]
	v_mad_u64_u32 v[30:31], s[46:47], v219, s85, v[6:7]
	v_mad_u64_u32 v[32:33], s[46:47], v218, s85, v[6:7]
	v_mad_u64_u32 v[34:35], s[46:47], v221, s85, v[6:7]
	v_mad_u64_u32 v[36:37], s[46:47], v220, s85, v[6:7]
	v_mad_u64_u32 v[40:41], s[46:47], v223, s85, v[6:7]
	v_mad_u64_u32 v[42:43], s[46:47], v222, s85, v[6:7]
	v_mad_u64_u32 v[44:45], s[46:47], v225, s85, v[6:7]
	v_mad_u64_u32 v[46:47], s[46:47], v224, s85, v[6:7]
	v_mad_u64_u32 v[48:49], s[46:47], v227, s85, v[6:7]
	v_mad_u64_u32 v[50:51], s[46:47], v226, s85, v[6:7]
	v_mad_u64_u32 v[52:53], s[46:47], v229, s85, v[6:7]
	v_mad_u64_u32 v[54:55], s[46:47], v228, s85, v[6:7]
	s_waitcnt vmcnt(31)
	ds_write_b32 v22, v17
	s_waitcnt vmcnt(30)
	ds_write_b32 v24, v21
	s_waitcnt vmcnt(29)
	ds_write_b32 v26, v39
	s_waitcnt vmcnt(28)
	ds_write_b32 v28, v56
	s_waitcnt vmcnt(20)
	ds_write_b32 v30, v64
	ds_write_b32 v32, v57
	ds_write_b32 v34, v63
	ds_write_b32 v36, v58
	s_waitcnt vmcnt(16)
	ds_write_b32 v40, v67
	ds_write_b32 v42, v59
	ds_write_b32 v44, v66
	ds_write_b32 v46, v60
	ds_write_b32 v48, v65
	ds_write_b32 v50, v61
	ds_write_b32 v52, v0
	ds_write_b32 v54, v62
	v_mad_u64_u32 v[100:101], s[46:47], v159, s85, v[6:7]
	v_mad_u64_u32 v[102:103], s[46:47], v150, s85, v[6:7]
	v_mad_u64_u32 v[104:105], s[46:47], v161, s85, v[6:7]
	v_mad_u64_u32 v[106:107], s[46:47], v152, s85, v[6:7]
	v_mad_u64_u32 v[108:109], s[46:47], v163, s85, v[6:7]
	v_mad_u64_u32 v[110:111], s[46:47], v154, s85, v[6:7]
	v_mad_u64_u32 v[112:113], s[46:47], v165, s85, v[6:7]
	v_mad_u64_u32 v[114:115], s[46:47], v156, s85, v[6:7]
	v_mad_u64_u32 v[118:119], s[46:47], v167, s85, v[6:7]
	v_mad_u64_u32 v[120:121], s[46:47], v158, s85, v[6:7]
	v_mad_u64_u32 v[122:123], s[46:47], v169, s85, v[6:7]
	v_mad_u64_u32 v[124:125], s[46:47], v160, s85, v[6:7]
	v_mad_u64_u32 v[126:127], s[46:47], v183, s85, v[6:7]
	v_mad_u64_u32 v[128:129], s[46:47], v162, s85, v[6:7]
	v_mad_u64_u32 v[130:131], s[46:47], v185, s85, v[6:7]
	v_mad_u64_u32 v[132:133], s[46:47], v164, s85, v[6:7]
	s_waitcnt vmcnt(15)
; __device__ __forceinline__ unsigned cvt_pk_bf16(float lo, float hi) { unsigned r; asm volatile("v_cvt_pk_bf16_f32 %0, %1, %2" : "=v"(r) : "v"(lo), "v"(hi)); return r; }
; #define LAS __attribute__((address_space(3)))
; #define LDS_WAIT() asm volatile("s_waitcnt lgkmcnt(0)" ::: "memory")
;     ...
;     for (int i = 0; i < 32; ++i) { const int kk = 2 * i + (lane >> 5); scr[kk * 33 + (lane & 31)] = W[(size_t)(k0 + kk) * N + n0 + (lane & 31)]; }
;     LDS_WAIT(); asm volatile("" ::: "memory");
;     const int c = lane & 7;
; #pragma unroll
;     for (int j = 0; j < 4; ++j) { const int n = (lane >> 3) + 8 * j; const LAS float* s = scr + (8 * c) * 33 + n;
;         u32x4 o; o.x = cvt_pk_bf16(s[0 * 33], s[1 * 33]); o.y = cvt_pk_bf16(s[2 * 33], s[3 * 33]); o.z = cvt_pk_bf16(s[4 * 33], s[5 * 33]); o.w = cvt_pk_bf16(s[6 * 33], s[7 * 33]);
;         *(u32x4*)(WT + (size_t)(dn0 + n) * ldo + koff + k0 + 8 * c) = o; }
;     LDS_WAIT(); asm volatile("" ::: "memory");
	ds_write_b32 v100, v97
	s_waitcnt vmcnt(14)
	ds_write_b32 v102, v99
	s_waitcnt vmcnt(13)
	ds_write_b32 v104, v117
	s_waitcnt vmcnt(12)
	ds_write_b32 v106, v96
	s_waitcnt vmcnt(4)
	ds_write_b32 v108, v136
	ds_write_b32 v110, v135
	ds_write_b32 v112, v153
	ds_write_b32 v114, v98
	s_waitcnt vmcnt(0)
	ds_write_b32 v118, v157
	ds_write_b32 v120, v137
	ds_write_b32 v122, v138
	ds_write_b32 v124, v116
	ds_write_b32 v126, v155
	ds_write_b32 v128, v151
	ds_write_b32 v130, v94
	ds_write_b32 v132, v134
	s_lshl_b64 s[38:39], s[38:39], 1
	v_readlane_b32 s41, v251, 18
	s_waitcnt lgkmcnt(0)
	s_add_u32 s38, s41, s38
	v_readlane_b32 s41, v251, 19
	s_addc_u32 s39, s41, s39
	s_lshl_b32 s3, s3, 1
	ds_read2_b32 v[14:15], v9 offset1:33
	s_add_u32 s38, s38, s3
	s_waitcnt lgkmcnt(0)
	v_cvt_pk_bf16_f32 v14, v14, v15
	ds_read2_b32 v[16:17], v9 offset0:66 offset1:99
	v_lshlrev_b32_e32 v0, 1, v8
	v_or_b32_e32 v5, s2, v7
	s_addc_u32 s39, s39, 0
	s_waitcnt lgkmcnt(0)
	v_cvt_pk_bf16_f32 v15, v16, v17
	ds_read2_b32 v[16:17], v9 offset0:132 offset1:165
	v_lshl_add_u64 v[24:25], s[38:39], 0, v[0:1]
	v_lshlrev_b32_e32 v0, 12, v5
	s_waitcnt lgkmcnt(0)
	v_cvt_pk_bf16_f32 v16, v16, v17
	ds_read2_b32 v[22:23], v9 offset0:198 offset1:231
	s_waitcnt lgkmcnt(0)
	v_cvt_pk_bf16_f32 v17, v22, v23
	v_lshl_add_u64 v[26:27], v[24:25], 0, v[0:1]
	ds_read2_b32 v[22:23], v9 offset0:8 offset1:41
	global_store_dwordx4 v[26:27], v[14:17], off sc1
	v_or_b32_e32 v0, s2, v18
	v_lshlrev_b32_e32 v0, 12, v0
	s_waitcnt lgkmcnt(0)
	v_cvt_pk_bf16_f32 v14, v22, v23
	ds_read2_b32 v[16:17], v9 offset0:74 offset1:107
	s_waitcnt lgkmcnt(0)
	v_cvt_pk_bf16_f32 v15, v16, v17
	ds_read2_b32 v[16:17], v9 offset0:140 offset1:173
	s_waitcnt lgkmcnt(0)
	v_cvt_pk_bf16_f32 v16, v16, v17
	ds_read2_b32 v[22:23], v9 offset0:206 offset1:239
	s_waitcnt lgkmcnt(0)
	v_cvt_pk_bf16_f32 v17, v22, v23
	v_lshl_add_u64 v[26:27], v[24:25], 0, v[0:1]
	ds_read2_b32 v[22:23], v9 offset0:16 offset1:49
	global_store_dwordx4 v[26:27], v[14:17], off sc1
	v_or_b32_e32 v0, s2, v19
	v_lshlrev_b32_e32 v0, 12, v0
	s_waitcnt lgkmcnt(0)
	v_cvt_pk_bf16_f32 v14, v22, v23
	ds_read2_b32 v[16:17], v9 offset0:82 offset1:115
	s_waitcnt lgkmcnt(0)
	v_cvt_pk_bf16_f32 v15, v16, v17
	ds_read2_b32 v[16:17], v9 offset0:148 offset1:181
	s_waitcnt lgkmcnt(0)
	v_cvt_pk_bf16_f32 v16, v16, v17
	ds_read2_b32 v[22:23], v9 offset0:214 offset1:247
	s_waitcnt lgkmcnt(0)
	v_cvt_pk_bf16_f32 v17, v22, v23
	v_lshl_add_u64 v[26:27], v[24:25], 0, v[0:1]
	ds_read2_b32 v[22:23], v9 offset0:24 offset1:57
	global_store_dwordx4 v[26:27], v[14:17], off sc1
	v_or_b32_e32 v0, s2, v20
	v_lshlrev_b32_e32 v0, 12, v0
	s_waitcnt lgkmcnt(0)
	v_cvt_pk_bf16_f32 v14, v22, v23
	ds_read2_b32 v[16:17], v9 offset0:90 offset1:123
	s_waitcnt lgkmcnt(0)
	v_cvt_pk_bf16_f32 v15, v16, v17
	ds_read2_b32 v[16:17], v9 offset0:156 offset1:189
	s_waitcnt lgkmcnt(0)
	v_cvt_pk_bf16_f32 v16, v16, v17
	ds_read2_b32 v[22:23], v9 offset0:222 offset1:255
	s_waitcnt lgkmcnt(0)
	v_cvt_pk_bf16_f32 v17, v22, v23
	v_lshl_add_u64 v[22:23], v[24:25], 0, v[0:1]
	global_store_dwordx4 v[22:23], v[14:17], off sc1
	s_waitcnt lgkmcnt(0)
	v_readlane_b32 s70, v253, 44
	v_readlane_b32 s71, v253, 45
	s_mov_b32 s48, 0x3a000000

; #define LDS_WAIT() asm volatile("s_waitcnt lgkmcnt(0)" ::: "memory")
;     ...
; #pragma unroll 8
;     for (int i = 0; i < 32; ++i) { const int kk = 2 * i + (lane >> 5); scr[kk * 33 + (lane & 31)] = W[(size_t)(k0 + kk) * N + n0 + (lane & 31)]; }
;     LDS_WAIT(); asm volatile("" ::: "memory");
.LBB0_489:
	s_lshl_b32 s46, s43, 1
	s_lshl_b32 s45, s41, 1
	v_or_b32_e32 v0, s46, v16
	s_add_i32 s49, s46, 4
	s_add_i32 s48, s45, 4
	s_add_i32 s50, s45, 8
	s_add_i32 s51, s46, 8
	v_lshlrev_b64 v[40:41], 13, v[0:1]
	v_or_b32_e32 v0, s49, v16
	v_mov_b32_e32 v23, v1
	v_mov_b32_e32 v25, v1
	v_mov_b32_e32 v27, v1
	v_or_b32_e32 v22, s45, v5
	s_add_i32 s52, s45, 12
	s_add_i32 s53, s46, 12
	s_add_i32 s54, s45, 16
	s_add_i32 s56, s45, 20
	s_add_i32 s58, s45, 24
	s_add_i32 s60, s45, 28
	v_or_b32_e32 v24, s48, v5
	v_or_b32_e32 v26, s50, v5
	v_lshlrev_b64 v[42:43], 13, v[0:1]
	v_or_b32_e32 v0, s51, v16
	v_mov_b32_e32 v29, v1
	v_mov_b32_e32 v31, v1
	v_mov_b32_e32 v33, v1
	v_mov_b32_e32 v35, v1
	v_mov_b32_e32 v37, v1
	s_add_i32 s55, s46, 16
	v_lshlrev_b64 v[22:23], 13, v[22:23]
	v_or_b32_e32 v28, s52, v5
	v_or_b32_e32 v30, s54, v5
	v_or_b32_e32 v32, s56, v5
	v_or_b32_e32 v34, s58, v5
	v_or_b32_e32 v36, s60, v5
	v_lshl_add_u64 v[40:41], v[14:15], 0, v[40:41]
	v_lshlrev_b64 v[24:25], 13, v[24:25]
	v_lshlrev_b64 v[26:27], 13, v[26:27]
	v_lshlrev_b64 v[44:45], 13, v[0:1]
	v_or_b32_e32 v0, s53, v16
	s_add_i32 s57, s46, 20
	v_lshl_add_u64 v[22:23], v[14:15], 0, v[22:23]
	v_lshlrev_b64 v[28:29], 13, v[28:29]
	v_lshlrev_b64 v[30:31], 13, v[30:31]
	v_lshlrev_b64 v[32:33], 13, v[32:33]
	v_lshlrev_b64 v[34:35], 13, v[34:35]
	v_lshlrev_b64 v[36:37], 13, v[36:37]
	v_lshl_add_u64 v[42:43], v[14:15], 0, v[42:43]
	v_lshl_add_u64 v[24:25], v[14:15], 0, v[24:25]
	v_lshl_add_u64 v[26:27], v[14:15], 0, v[26:27]
	global_load_dword v17, v[40:41], off nt
	global_load_dword v21, v[22:23], off nt
	v_lshlrev_b64 v[40:41], 13, v[0:1]
	v_or_b32_e32 v0, s55, v16
	s_add_i32 s59, s46, 24
	v_lshl_add_u64 v[28:29], v[14:15], 0, v[28:29]
	v_lshl_add_u64 v[30:31], v[14:15], 0, v[30:31]
	v_lshl_add_u64 v[32:33], v[14:15], 0, v[32:33]
	v_lshl_add_u64 v[34:35], v[14:15], 0, v[34:35]
	v_lshl_add_u64 v[36:37], v[14:15], 0, v[36:37]
	global_load_dword v39, v[42:43], off nt
	global_load_dword v56, v[24:25], off nt
	global_load_dword v57, v[26:27], off nt
	global_load_dword v58, v[28:29], off nt
	global_load_dword v59, v[30:31], off nt
	global_load_dword v60, v[32:33], off nt
	global_load_dword v61, v[34:35], off nt
	global_load_dword v62, v[36:37], off nt
	v_lshl_add_u64 v[24:25], v[14:15], 0, v[40:41]
	v_lshlrev_b64 v[26:27], 13, v[0:1]
	v_or_b32_e32 v0, s57, v16
	s_add_i32 s61, s46, 28
	v_lshl_add_u64 v[22:23], v[14:15], 0, v[44:45]
	global_load_dword v63, v[24:25], off nt
	global_load_dword v64, v[22:23], off nt
	v_lshlrev_b64 v[24:25], 13, v[0:1]
	v_or_b32_e32 v0, s59, v16
	v_lshl_add_u64 v[22:23], v[14:15], 0, v[26:27]
	v_lshlrev_b64 v[26:27], 13, v[0:1]
	v_or_b32_e32 v0, s61, v16
	v_lshlrev_b64 v[28:29], 13, v[0:1]
	v_lshl_add_u64 v[28:29], v[14:15], 0, v[28:29]
	v_lshl_add_u64 v[24:25], v[14:15], 0, v[24:25]
	v_lshl_add_u64 v[26:27], v[14:15], 0, v[26:27]
	global_load_dword v0, v[28:29], off nt
	global_load_dword v65, v[26:27], off nt
	global_load_dword v66, v[24:25], off nt
	global_load_dword v67, v[22:23], off nt
	v_or_b32_e32 v214, s45, v3
	v_or_b32_e32 v215, s46, v2
	v_or_b32_e32 v216, s48, v3
	v_or_b32_e32 v217, s49, v2
	v_or_b32_e32 v218, s50, v3
	v_or_b32_e32 v219, s51, v2
	v_or_b32_e32 v220, s52, v3
	v_or_b32_e32 v221, s53, v2
	v_or_b32_e32 v222, s54, v3
	v_or_b32_e32 v223, s55, v2
	v_or_b32_e32 v224, s56, v3
	v_or_b32_e32 v225, s57, v2
	v_or_b32_e32 v226, s58, v3
	v_or_b32_e32 v227, s59, v2
	v_or_b32_e32 v228, s60, v3
	v_or_b32_e32 v229, s61, v2
	s_add_i32 s43, s43, 16
	s_add_i32 s41, s41, 16
	s_add_i32 s44, s44, -16
	s_cmp_lg_u32 s44, 0
	v_mov_b32_e32 v95, 0
	s_lshl_b32 s46, s43, 1
	s_lshl_b32 s45, s41, 1
	v_or_b32_e32 v94, s46, v16
	s_add_i32 s49, s46, 4
	s_add_i32 s48, s45, 4
	s_add_i32 s50, s45, 8
	s_add_i32 s51, s46, 8
	v_lshlrev_b64 v[118:119], 13, v[94:95]
	v_or_b32_e32 v94, s49, v16
	v_mov_b32_e32 v101, v95
	v_mov_b32_e32 v103, v95
	v_mov_b32_e32 v105, v95
	v_or_b32_e32 v100, s45, v5
	s_add_i32 s52, s45, 12
	s_add_i32 s53, s46, 12
	s_add_i32 s54, s45, 16
	s_add_i32 s56, s45, 20
	s_add_i32 s58, s45, 24
	s_add_i32 s60, s45, 28
	v_or_b32_e32 v102, s48, v5
	v_or_b32_e32 v104, s50, v5
	v_lshlrev_b64 v[120:121], 13, v[94:95]
	v_or_b32_e32 v94, s51, v16
	v_mov_b32_e32 v107, v95
	v_mov_b32_e32 v109, v95
	v_mov_b32_e32 v111, v95
	v_mov_b32_e32 v113, v95
	v_mov_b32_e32 v115, v95
	s_add_i32 s55, s46, 16
	v_lshlrev_b64 v[100:101], 13, v[100:101]
	v_or_b32_e32 v106, s52, v5
	v_or_b32_e32 v108, s54, v5
	v_or_b32_e32 v110, s56, v5
	v_or_b32_e32 v112, s58, v5
	v_or_b32_e32 v114, s60, v5
	v_lshl_add_u64 v[118:119], v[14:15], 0, v[118:119]
	v_lshlrev_b64 v[102:103], 13, v[102:103]
	v_lshlrev_b64 v[104:105], 13, v[104:105]
	v_lshlrev_b64 v[122:123], 13, v[94:95]
	v_or_b32_e32 v94, s53, v16
	s_add_i32 s57, s46, 20
	v_lshl_add_u64 v[100:101], v[14:15], 0, v[100:101]
	v_lshlrev_b64 v[106:107], 13, v[106:107]
	v_lshlrev_b64 v[108:109], 13, v[108:109]
	v_lshlrev_b64 v[110:111], 13, v[110:111]
	v_lshlrev_b64 v[112:113], 13, v[112:113]
	v_lshlrev_b64 v[114:115], 13, v[114:115]
	v_lshl_add_u64 v[120:121], v[14:15], 0, v[120:121]
	v_lshl_add_u64 v[102:103], v[14:15], 0, v[102:103]
	v_lshl_add_u64 v[104:105], v[14:15], 0, v[104:105]
	global_load_dword v97, v[118:119], off nt
	global_load_dword v99, v[100:101], off nt
	v_lshlrev_b64 v[118:119], 13, v[94:95]
	v_or_b32_e32 v94, s55, v16
	s_add_i32 s59, s46, 24
	v_lshl_add_u64 v[106:107], v[14:15], 0, v[106:107]
	v_lshl_add_u64 v[108:109], v[14:15], 0, v[108:109]
	v_lshl_add_u64 v[110:111], v[14:15], 0, v[110:111]
	v_lshl_add_u64 v[112:113], v[14:15], 0, v[112:113]
	v_lshl_add_u64 v[114:115], v[14:15], 0, v[114:115]
	global_load_dword v117, v[120:121], off nt
; #define LDS_WAIT() asm volatile("s_waitcnt lgkmcnt(0)" ::: "memory")
;     ...
;     for (int i = 0; i < 32; ++i) { const int kk = 2 * i + (lane >> 5); scr[kk * 33 + (lane & 31)] = W[(size_t)(k0 + kk) * N + n0 + (lane & 31)]; }
;     LDS_WAIT(); asm volatile("" ::: "memory");
	global_load_dword v96, v[102:103], off nt
	global_load_dword v135, v[104:105], off nt
	global_load_dword v98, v[106:107], off nt
	global_load_dword v137, v[108:109], off nt
	global_load_dword v116, v[110:111], off nt
	global_load_dword v151, v[112:113], off nt
	global_load_dword v134, v[114:115], off nt
	v_lshl_add_u64 v[102:103], v[14:15], 0, v[118:119]
	v_lshlrev_b64 v[104:105], 13, v[94:95]
	v_or_b32_e32 v94, s57, v16
	s_add_i32 s61, s46, 28
	v_lshl_add_u64 v[100:101], v[14:15], 0, v[122:123]
	global_load_dword v153, v[102:103], off nt
	global_load_dword v136, v[100:101], off nt
	v_lshlrev_b64 v[102:103], 13, v[94:95]
	v_or_b32_e32 v94, s59, v16
	v_lshl_add_u64 v[100:101], v[14:15], 0, v[104:105]
	v_lshlrev_b64 v[104:105], 13, v[94:95]
	v_or_b32_e32 v94, s61, v16
	v_lshlrev_b64 v[106:107], 13, v[94:95]
	v_lshl_add_u64 v[106:107], v[14:15], 0, v[106:107]
	v_lshl_add_u64 v[102:103], v[14:15], 0, v[102:103]
	v_lshl_add_u64 v[104:105], v[14:15], 0, v[104:105]
	global_load_dword v94, v[106:107], off nt
	global_load_dword v155, v[104:105], off nt
	global_load_dword v138, v[102:103], off nt
	global_load_dword v157, v[100:101], off nt
	v_or_b32_e32 v150, s45, v3
	v_or_b32_e32 v159, s46, v2
	v_or_b32_e32 v152, s48, v3
	v_or_b32_e32 v161, s49, v2
	v_or_b32_e32 v154, s50, v3
	v_or_b32_e32 v163, s51, v2
	v_or_b32_e32 v156, s52, v3
	v_or_b32_e32 v165, s53, v2
	v_or_b32_e32 v158, s54, v3
	v_or_b32_e32 v167, s55, v2
	v_or_b32_e32 v160, s56, v3
	v_or_b32_e32 v169, s57, v2
	v_or_b32_e32 v162, s58, v3
	v_or_b32_e32 v183, s59, v2
	v_or_b32_e32 v164, s60, v3
	v_or_b32_e32 v185, s61, v2
	s_add_i32 s43, s43, 16
	s_add_i32 s41, s41, 16
	s_add_i32 s44, s44, -16
	s_cmp_lg_u32 s44, 0
	v_mad_u64_u32 v[22:23], s[46:47], v215, s85, v[6:7]
	v_mad_u64_u32 v[24:25], s[46:47], v214, s85, v[6:7]
	v_mad_u64_u32 v[26:27], s[46:47], v217, s85, v[6:7]
	v_mad_u64_u32 v[28:29], s[46:47], v216, s85, v[6:7]
	v_mad_u64_u32 v[30:31], s[46:47], v219, s85, v[6:7]
	v_mad_u64_u32 v[32:33], s[46:47], v218, s85, v[6:7]
	v_mad_u64_u32 v[34:35], s[46:47], v221, s85, v[6:7]
	v_mad_u64_u32 v[36:37], s[46:47], v220, s85, v[6:7]
	v_mad_u64_u32 v[40:41], s[46:47], v223, s85, v[6:7]
	v_mad_u64_u32 v[42:43], s[46:47], v222, s85, v[6:7]
	v_mad_u64_u32 v[44:45], s[46:47], v225, s85, v[6:7]
	v_mad_u64_u32 v[46:47], s[46:47], v224, s85, v[6:7]
	v_mad_u64_u32 v[48:49], s[46:47], v227, s85, v[6:7]
	v_mad_u64_u32 v[50:51], s[46:47], v226, s85, v[6:7]
	v_mad_u64_u32 v[52:53], s[46:47], v229, s85, v[6:7]
	v_mad_u64_u32 v[54:55], s[46:47], v228, s85, v[6:7]
	s_waitcnt vmcnt(31)
	ds_write_b32 v22, v17
	s_waitcnt vmcnt(30)
	ds_write_b32 v24, v21
	s_waitcnt vmcnt(29)
	ds_write_b32 v26, v39
	s_waitcnt vmcnt(28)
	ds_write_b32 v28, v56
	s_waitcnt vmcnt(20)
	ds_write_b32 v30, v64
	ds_write_b32 v32, v57
	ds_write_b32 v34, v63
	ds_write_b32 v36, v58
	s_waitcnt vmcnt(16)
	ds_write_b32 v40, v67
	ds_write_b32 v42, v59
	ds_write_b32 v44, v66
	ds_write_b32 v46, v60
	ds_write_b32 v48, v65
	ds_write_b32 v50, v61
	ds_write_b32 v52, v0
	ds_write_b32 v54, v62
	v_mad_u64_u32 v[100:101], s[46:47], v159, s85, v[6:7]
	v_mad_u64_u32 v[102:103], s[46:47], v150, s85, v[6:7]
	v_mad_u64_u32 v[104:105], s[46:47], v161, s85, v[6:7]
	v_mad_u64_u32 v[106:107], s[46:47], v152, s85, v[6:7]
	v_mad_u64_u32 v[108:109], s[46:47], v163, s85, v[6:7]
	v_mad_u64_u32 v[110:111], s[46:47], v154, s85, v[6:7]
	v_mad_u64_u32 v[112:113], s[46:47], v165, s85, v[6:7]
	v_mad_u64_u32 v[114:115], s[46:47], v156, s85, v[6:7]
	v_mad_u64_u32 v[118:119], s[46:47], v167, s85, v[6:7]
	v_mad_u64_u32 v[120:121], s[46:47], v158, s85, v[6:7]
	v_mad_u64_u32 v[122:123], s[46:47], v169, s85, v[6:7]
	v_mad_u64_u32 v[124:125], s[46:47], v160, s85, v[6:7]
	v_mad_u64_u32 v[126:127], s[46:47], v183, s85, v[6:7]
	v_mad_u64_u32 v[128:129], s[46:47], v162, s85, v[6:7]
	v_mad_u64_u32 v[130:131], s[46:47], v185, s85, v[6:7]
	v_mad_u64_u32 v[132:133], s[46:47], v164, s85, v[6:7]
	s_waitcnt vmcnt(15)
; __device__ __forceinline__ unsigned cvt_pk_bf16(float lo, float hi) { unsigned r; asm volatile("v_cvt_pk_bf16_f32 %0, %1, %2" : "=v"(r) : "v"(lo), "v"(hi)); return r; }
; #define LAS __attribute__((address_space(3)))
; #define LDS_WAIT() asm volatile("s_waitcnt lgkmcnt(0)" ::: "memory")
;     ...
;     for (int i = 0; i < 32; ++i) { const int kk = 2 * i + (lane >> 5); scr[kk * 33 + (lane & 31)] = W[(size_t)(k0 + kk) * N + n0 + (lane & 31)]; }
;     LDS_WAIT(); asm volatile("" ::: "memory");
;     const int c = lane & 7;
; #pragma unroll
;     for (int j = 0; j < 4; ++j) { const int n = (lane >> 3) + 8 * j; const LAS float* s = scr + (8 * c) * 33 + n;
;         u32x4 o; o.x = cvt_pk_bf16(s[0 * 33], s[1 * 33]); o.y = cvt_pk_bf16(s[2 * 33], s[3 * 33]); o.z = cvt_pk_bf16(s[4 * 33], s[5 * 33]); o.w = cvt_pk_bf16(s[6 * 33], s[7 * 33]);
;         *(u32x4*)(WT + (size_t)(dn0 + n) * ldo + koff + k0 + 8 * c) = o; }
;     LDS_WAIT(); asm volatile("" ::: "memory");
	ds_write_b32 v100, v97
	s_waitcnt vmcnt(14)
	ds_write_b32 v102, v99
	s_waitcnt vmcnt(13)
	ds_write_b32 v104, v117
	s_waitcnt vmcnt(12)
	ds_write_b32 v106, v96
	s_waitcnt vmcnt(4)
	ds_write_b32 v108, v136
	ds_write_b32 v110, v135
	ds_write_b32 v112, v153
	ds_write_b32 v114, v98
	s_waitcnt vmcnt(0)
	ds_write_b32 v118, v157
	ds_write_b32 v120, v137
	ds_write_b32 v122, v138
	ds_write_b32 v124, v116
	ds_write_b32 v126, v155
	ds_write_b32 v128, v151
	ds_write_b32 v130, v94
	ds_write_b32 v132, v134
	s_add_u32 s38, s28, s38
	s_waitcnt lgkmcnt(0)
	s_addc_u32 s39, s29, s39
	s_lshl_b32 s3, s3, 1
	s_add_u32 s38, s38, s3
	ds_read2_b32 v[14:15], v9 offset1:33
	v_lshlrev_b32_e32 v0, 1, v8
	s_addc_u32 s39, s39, 0
	s_waitcnt lgkmcnt(0)
	v_cvt_pk_bf16_f32 v14, v14, v15
	ds_read2_b32 v[16:17], v9 offset0:66 offset1:99
	v_or_b32_e32 v5, s2, v7
	v_lshl_add_u64 v[24:25], s[38:39], 0, v[0:1]
	s_mov_b64 s[38:39], 0xd400800
	s_waitcnt lgkmcnt(0)
	v_cvt_pk_bf16_f32 v15, v16, v17
	ds_read2_b32 v[16:17], v9 offset0:132 offset1:165
	v_lshlrev_b32_e32 v0, 12, v5
	v_lshl_add_u64 v[24:25], v[24:25], 0, s[38:39]
	s_waitcnt lgkmcnt(0)
	v_cvt_pk_bf16_f32 v16, v16, v17
	ds_read2_b32 v[22:23], v9 offset0:198 offset1:231
	s_waitcnt lgkmcnt(0)
	v_cvt_pk_bf16_f32 v17, v22, v23
	v_lshl_add_u64 v[26:27], v[24:25], 0, v[0:1]
	ds_read2_b32 v[22:23], v9 offset0:8 offset1:41
	global_store_dwordx4 v[26:27], v[14:17], off sc1
	v_or_b32_e32 v0, s2, v18
	v_lshlrev_b32_e32 v0, 12, v0
	s_waitcnt lgkmcnt(0)
	v_cvt_pk_bf16_f32 v14, v22, v23
	ds_read2_b32 v[16:17], v9 offset0:74 offset1:107
	s_waitcnt lgkmcnt(0)
	v_cvt_pk_bf16_f32 v15, v16, v17
	ds_read2_b32 v[16:17], v9 offset0:140 offset1:173
	s_waitcnt lgkmcnt(0)
	v_cvt_pk_bf16_f32 v16, v16, v17
	ds_read2_b32 v[22:23], v9 offset0:206 offset1:239
	s_waitcnt lgkmcnt(0)
	v_cvt_pk_bf16_f32 v17, v22, v23
	v_lshl_add_u64 v[26:27], v[24:25], 0, v[0:1]
	ds_read2_b32 v[22:23], v9 offset0:16 offset1:49
	global_store_dwordx4 v[26:27], v[14:17], off sc1
	v_or_b32_e32 v0, s2, v19
	v_lshlrev_b32_e32 v0, 12, v0
	s_waitcnt lgkmcnt(0)
	v_cvt_pk_bf16_f32 v14, v22, v23
	ds_read2_b32 v[16:17], v9 offset0:82 offset1:115
	s_waitcnt lgkmcnt(0)
	v_cvt_pk_bf16_f32 v15, v16, v17
	ds_read2_b32 v[16:17], v9 offset0:148 offset1:181
	s_waitcnt lgkmcnt(0)
	v_cvt_pk_bf16_f32 v16, v16, v17
	ds_read2_b32 v[22:23], v9 offset0:214 offset1:247
	s_waitcnt lgkmcnt(0)
	v_cvt_pk_bf16_f32 v17, v22, v23
	v_lshl_add_u64 v[26:27], v[24:25], 0, v[0:1]
	ds_read2_b32 v[22:23], v9 offset0:24 offset1:57
	global_store_dwordx4 v[26:27], v[14:17], off sc1
	v_or_b32_e32 v0, s2, v20
	v_lshlrev_b32_e32 v0, 12, v0
	s_waitcnt lgkmcnt(0)
	v_cvt_pk_bf16_f32 v14, v22, v23
	ds_read2_b32 v[16:17], v9 offset0:90 offset1:123
	s_waitcnt lgkmcnt(0)
	v_cvt_pk_bf16_f32 v15, v16, v17
	ds_read2_b32 v[16:17], v9 offset0:156 offset1:189
	s_waitcnt lgkmcnt(0)
	v_cvt_pk_bf16_f32 v16, v16, v17
	ds_read2_b32 v[22:23], v9 offset0:222 offset1:255
	s_waitcnt lgkmcnt(0)
	v_cvt_pk_bf16_f32 v17, v22, v23
	v_lshl_add_u64 v[22:23], v[24:25], 0, v[0:1]
	global_store_dwordx4 v[22:23], v[14:17], off sc1
	s_waitcnt lgkmcnt(0)
	v_readlane_b32 s70, v253, 44
	v_readlane_b32 s71, v253, 45
	s_mov_b32 s48, 0x3a000000

; #define LDS_WAIT() asm volatile("s_waitcnt lgkmcnt(0)" ::: "memory")
;     ...
; #pragma unroll 8
;     for (int i = 0; i < 32; ++i) { const int kk = 2 * i + (lane >> 5); scr[kk * 33 + (lane & 31)] = W[(size_t)(k0 + kk) * N + n0 + (lane & 31)]; }
;     LDS_WAIT(); asm volatile("" ::: "memory");
.LBB0_494:
	s_lshl_b32 s45, s41, 1
	s_lshl_b32 s44, s3, 1
	v_or_b32_e32 v0, s45, v16
	s_add_i32 s47, s45, 4
	s_add_i32 s46, s44, 4
	s_add_i32 s48, s44, 8
	s_add_i32 s49, s45, 8
	v_lshlrev_b64 v[40:41], 13, v[0:1]
	v_or_b32_e32 v0, s47, v16
	v_mov_b32_e32 v23, v1
	v_mov_b32_e32 v25, v1
	v_mov_b32_e32 v27, v1
	v_or_b32_e32 v22, s44, v5
	s_add_i32 s50, s44, 12
	s_add_i32 s51, s45, 12
	s_add_i32 s52, s44, 16
	s_add_i32 s54, s44, 20
	s_add_i32 s56, s44, 24
	s_add_i32 s58, s44, 28
	v_or_b32_e32 v24, s46, v5
	v_or_b32_e32 v26, s48, v5
	v_lshlrev_b64 v[42:43], 13, v[0:1]
	v_or_b32_e32 v0, s49, v16
	v_mov_b32_e32 v29, v1
	v_mov_b32_e32 v31, v1
	v_mov_b32_e32 v33, v1
	v_mov_b32_e32 v35, v1
	v_mov_b32_e32 v37, v1
	s_add_i32 s53, s45, 16
	v_lshlrev_b64 v[22:23], 13, v[22:23]
	v_or_b32_e32 v28, s50, v5
	v_or_b32_e32 v30, s52, v5
	v_or_b32_e32 v32, s54, v5
	v_or_b32_e32 v34, s56, v5
	v_or_b32_e32 v36, s58, v5
	v_lshl_add_u64 v[40:41], v[14:15], 0, v[40:41]
	v_lshlrev_b64 v[24:25], 13, v[24:25]
	v_lshlrev_b64 v[26:27], 13, v[26:27]
	v_lshlrev_b64 v[44:45], 13, v[0:1]
	v_or_b32_e32 v0, s51, v16
	s_add_i32 s55, s45, 20
	v_lshl_add_u64 v[22:23], v[14:15], 0, v[22:23]
	v_lshlrev_b64 v[28:29], 13, v[28:29]
	v_lshlrev_b64 v[30:31], 13, v[30:31]
	v_lshlrev_b64 v[32:33], 13, v[32:33]
	v_lshlrev_b64 v[34:35], 13, v[34:35]
	v_lshlrev_b64 v[36:37], 13, v[36:37]
	v_lshl_add_u64 v[42:43], v[14:15], 0, v[42:43]
	v_lshl_add_u64 v[24:25], v[14:15], 0, v[24:25]
	v_lshl_add_u64 v[26:27], v[14:15], 0, v[26:27]
	global_load_dword v17, v[40:41], off nt
	global_load_dword v21, v[22:23], off nt
	v_lshlrev_b64 v[40:41], 13, v[0:1]
	v_or_b32_e32 v0, s53, v16
	s_add_i32 s57, s45, 24
	v_lshl_add_u64 v[28:29], v[14:15], 0, v[28:29]
	v_lshl_add_u64 v[30:31], v[14:15], 0, v[30:31]
	v_lshl_add_u64 v[32:33], v[14:15], 0, v[32:33]
	v_lshl_add_u64 v[34:35], v[14:15], 0, v[34:35]
	v_lshl_add_u64 v[36:37], v[14:15], 0, v[36:37]
	global_load_dword v39, v[42:43], off nt
	global_load_dword v56, v[24:25], off nt
	global_load_dword v57, v[26:27], off nt
	global_load_dword v58, v[28:29], off nt
	global_load_dword v59, v[30:31], off nt
	global_load_dword v60, v[32:33], off nt
	global_load_dword v61, v[34:35], off nt
	global_load_dword v62, v[36:37], off nt
	v_lshl_add_u64 v[24:25], v[14:15], 0, v[40:41]
	v_lshlrev_b64 v[26:27], 13, v[0:1]
	v_or_b32_e32 v0, s55, v16
	s_add_i32 s59, s45, 28
	v_lshl_add_u64 v[22:23], v[14:15], 0, v[44:45]
	global_load_dword v63, v[24:25], off nt
	global_load_dword v64, v[22:23], off nt
	v_lshlrev_b64 v[24:25], 13, v[0:1]
	v_or_b32_e32 v0, s57, v16
	v_lshl_add_u64 v[22:23], v[14:15], 0, v[26:27]
	v_lshlrev_b64 v[26:27], 13, v[0:1]
	v_or_b32_e32 v0, s59, v16
	v_lshlrev_b64 v[28:29], 13, v[0:1]
	v_lshl_add_u64 v[28:29], v[14:15], 0, v[28:29]
	v_lshl_add_u64 v[24:25], v[14:15], 0, v[24:25]
	v_lshl_add_u64 v[26:27], v[14:15], 0, v[26:27]
	global_load_dword v0, v[28:29], off nt
	global_load_dword v65, v[26:27], off nt
	global_load_dword v66, v[24:25], off nt
	global_load_dword v67, v[22:23], off nt
	v_or_b32_e32 v214, s44, v3
	v_or_b32_e32 v215, s45, v2
	v_or_b32_e32 v216, s46, v3
	v_or_b32_e32 v217, s47, v2
	v_or_b32_e32 v218, s48, v3
	v_or_b32_e32 v219, s49, v2
	v_or_b32_e32 v220, s50, v3
	v_or_b32_e32 v221, s51, v2
	v_or_b32_e32 v222, s52, v3
	v_or_b32_e32 v223, s53, v2
	v_or_b32_e32 v224, s54, v3
	v_or_b32_e32 v225, s55, v2
	v_or_b32_e32 v226, s56, v3
	v_or_b32_e32 v227, s57, v2
	v_or_b32_e32 v228, s58, v3
	v_or_b32_e32 v229, s59, v2
	s_add_i32 s41, s41, 16
	s_add_i32 s3, s3, 16
	s_add_i32 s43, s43, -16
	s_cmp_lg_u32 s43, 0
	v_mov_b32_e32 v95, 0
	s_lshl_b32 s45, s41, 1
	s_lshl_b32 s44, s3, 1
	v_or_b32_e32 v94, s45, v16
	s_add_i32 s47, s45, 4
	s_add_i32 s46, s44, 4
	s_add_i32 s48, s44, 8
	s_add_i32 s49, s45, 8
	v_lshlrev_b64 v[118:119], 13, v[94:95]
	v_or_b32_e32 v94, s47, v16
	v_mov_b32_e32 v101, v95
	v_mov_b32_e32 v103, v95
	v_mov_b32_e32 v105, v95
	v_or_b32_e32 v100, s44, v5
	s_add_i32 s50, s44, 12
	s_add_i32 s51, s45, 12
	s_add_i32 s52, s44, 16
	s_add_i32 s54, s44, 20
	s_add_i32 s56, s44, 24
	s_add_i32 s58, s44, 28
	v_or_b32_e32 v102, s46, v5
	v_or_b32_e32 v104, s48, v5
	v_lshlrev_b64 v[120:121], 13, v[94:95]
	v_or_b32_e32 v94, s49, v16
	v_mov_b32_e32 v107, v95
	v_mov_b32_e32 v109, v95
	v_mov_b32_e32 v111, v95
	v_mov_b32_e32 v113, v95
	v_mov_b32_e32 v115, v95
	s_add_i32 s53, s45, 16
	v_lshlrev_b64 v[100:101], 13, v[100:101]
	v_or_b32_e32 v106, s50, v5
	v_or_b32_e32 v108, s52, v5
	v_or_b32_e32 v110, s54, v5
	v_or_b32_e32 v112, s56, v5
	v_or_b32_e32 v114, s58, v5
	v_lshl_add_u64 v[118:119], v[14:15], 0, v[118:119]
	v_lshlrev_b64 v[102:103], 13, v[102:103]
	v_lshlrev_b64 v[104:105], 13, v[104:105]
	v_lshlrev_b64 v[122:123], 13, v[94:95]
	v_or_b32_e32 v94, s51, v16
	s_add_i32 s55, s45, 20
	v_lshl_add_u64 v[100:101], v[14:15], 0, v[100:101]
	v_lshlrev_b64 v[106:107], 13, v[106:107]
	v_lshlrev_b64 v[108:109], 13, v[108:109]
	v_lshlrev_b64 v[110:111], 13, v[110:111]
	v_lshlrev_b64 v[112:113], 13, v[112:113]
	v_lshlrev_b64 v[114:115], 13, v[114:115]
	v_lshl_add_u64 v[120:121], v[14:15], 0, v[120:121]
	v_lshl_add_u64 v[102:103], v[14:15], 0, v[102:103]
	v_lshl_add_u64 v[104:105], v[14:15], 0, v[104:105]
	global_load_dword v97, v[118:119], off nt
	global_load_dword v99, v[100:101], off nt
	v_lshlrev_b64 v[118:119], 13, v[94:95]
	v_or_b32_e32 v94, s53, v16
	s_add_i32 s57, s45, 24
	v_lshl_add_u64 v[106:107], v[14:15], 0, v[106:107]
	v_lshl_add_u64 v[108:109], v[14:15], 0, v[108:109]
	v_lshl_add_u64 v[110:111], v[14:15], 0, v[110:111]
	v_lshl_add_u64 v[112:113], v[14:15], 0, v[112:113]
	v_lshl_add_u64 v[114:115], v[14:15], 0, v[114:115]
	global_load_dword v117, v[120:121], off nt
; __device__ __forceinline__ unsigned cvt_pk_bf16(float lo, float hi) { unsigned r; asm volatile("v_cvt_pk_bf16_f32 %0, %1, %2" : "=v"(r) : "v"(lo), "v"(hi)); return r; }
; #define LAS __attribute__((address_space(3)))
; #define LDS_WAIT() asm volatile("s_waitcnt lgkmcnt(0)" ::: "memory")
;     ...
;     for (int i = 0; i < 32; ++i) { const int kk = 2 * i + (lane >> 5); scr[kk * 33 + (lane & 31)] = W[(size_t)(k0 + kk) * N + n0 + (lane & 31)]; }
;     LDS_WAIT(); asm volatile("" ::: "memory");
;     const int c = lane & 7;
; #pragma unroll
;     for (int j = 0; j < 4; ++j) { const int n = (lane >> 3) + 8 * j; const LAS float* s = scr + (8 * c) * 33 + n;
;         u32x4 o; o.x = cvt_pk_bf16(s[0 * 33], s[1 * 33]); o.y = cvt_pk_bf16(s[2 * 33], s[3 * 33]); o.z = cvt_pk_bf16(s[4 * 33], s[5 * 33]); o.w = cvt_pk_bf16(s[6 * 33], s[7 * 33]);
;         *(u32x4*)(WT + (size_t)(dn0 + n) * ldo + koff + k0 + 8 * c) = o; }
;     LDS_WAIT(); asm volatile("" ::: "memory");
	global_load_dword v96, v[102:103], off nt
	global_load_dword v135, v[104:105], off nt
	global_load_dword v98, v[106:107], off nt
	global_load_dword v137, v[108:109], off nt
	global_load_dword v116, v[110:111], off nt
	global_load_dword v151, v[112:113], off nt
	global_load_dword v134, v[114:115], off nt
	v_lshl_add_u64 v[102:103], v[14:15], 0, v[118:119]
	v_lshlrev_b64 v[104:105], 13, v[94:95]
	v_or_b32_e32 v94, s55, v16
	s_add_i32 s59, s45, 28
	v_lshl_add_u64 v[100:101], v[14:15], 0, v[122:123]
	global_load_dword v153, v[102:103], off nt
	global_load_dword v136, v[100:101], off nt
	v_lshlrev_b64 v[102:103], 13, v[94:95]
	v_or_b32_e32 v94, s57, v16
	v_lshl_add_u64 v[100:101], v[14:15], 0, v[104:105]
	v_lshlrev_b64 v[104:105], 13, v[94:95]
	v_or_b32_e32 v94, s59, v16
	v_lshlrev_b64 v[106:107], 13, v[94:95]
	v_lshl_add_u64 v[106:107], v[14:15], 0, v[106:107]
	v_lshl_add_u64 v[102:103], v[14:15], 0, v[102:103]
	v_lshl_add_u64 v[104:105], v[14:15], 0, v[104:105]
	global_load_dword v94, v[106:107], off nt
	global_load_dword v155, v[104:105], off nt
	global_load_dword v138, v[102:103], off nt
	global_load_dword v157, v[100:101], off nt
	v_or_b32_e32 v150, s44, v3
	v_or_b32_e32 v159, s45, v2
	v_or_b32_e32 v152, s46, v3
	v_or_b32_e32 v161, s47, v2
	v_or_b32_e32 v154, s48, v3
	v_or_b32_e32 v163, s49, v2
	v_or_b32_e32 v156, s50, v3
	v_or_b32_e32 v165, s51, v2
	v_or_b32_e32 v158, s52, v3
	v_or_b32_e32 v167, s53, v2
	v_or_b32_e32 v160, s54, v3
	v_or_b32_e32 v169, s55, v2
	v_or_b32_e32 v162, s56, v3
	v_or_b32_e32 v183, s57, v2
	v_or_b32_e32 v164, s58, v3
	v_or_b32_e32 v185, s59, v2
	s_add_i32 s41, s41, 16
	s_add_i32 s3, s3, 16
	s_add_i32 s43, s43, -16
	s_cmp_lg_u32 s43, 0
	v_mad_u64_u32 v[22:23], s[44:45], v215, s85, v[6:7]
	v_mad_u64_u32 v[24:25], s[44:45], v214, s85, v[6:7]
	v_mad_u64_u32 v[26:27], s[44:45], v217, s85, v[6:7]
	v_mad_u64_u32 v[28:29], s[44:45], v216, s85, v[6:7]
	v_mad_u64_u32 v[30:31], s[44:45], v219, s85, v[6:7]
	v_mad_u64_u32 v[32:33], s[44:45], v218, s85, v[6:7]
	v_mad_u64_u32 v[34:35], s[44:45], v221, s85, v[6:7]
	v_mad_u64_u32 v[36:37], s[44:45], v220, s85, v[6:7]
	v_mad_u64_u32 v[40:41], s[44:45], v223, s85, v[6:7]
	v_mad_u64_u32 v[42:43], s[44:45], v222, s85, v[6:7]
	v_mad_u64_u32 v[44:45], s[44:45], v225, s85, v[6:7]
	v_mad_u64_u32 v[46:47], s[44:45], v224, s85, v[6:7]
	v_mad_u64_u32 v[48:49], s[44:45], v227, s85, v[6:7]
	v_mad_u64_u32 v[50:51], s[44:45], v226, s85, v[6:7]
	v_mad_u64_u32 v[52:53], s[44:45], v229, s85, v[6:7]
	v_mad_u64_u32 v[54:55], s[44:45], v228, s85, v[6:7]
	s_waitcnt vmcnt(31)
	ds_write_b32 v22, v17
	s_waitcnt vmcnt(30)
	ds_write_b32 v24, v21
	s_waitcnt vmcnt(29)
	ds_write_b32 v26, v39
	s_waitcnt vmcnt(28)
	ds_write_b32 v28, v56
	s_waitcnt vmcnt(20)
	ds_write_b32 v30, v64
	ds_write_b32 v32, v57
	ds_write_b32 v34, v63
	ds_write_b32 v36, v58
	s_waitcnt vmcnt(16)
	ds_write_b32 v40, v67
	ds_write_b32 v42, v59
	ds_write_b32 v44, v66
	ds_write_b32 v46, v60
	ds_write_b32 v48, v65
	ds_write_b32 v50, v61
	ds_write_b32 v52, v0
	ds_write_b32 v54, v62
	v_mad_u64_u32 v[100:101], s[44:45], v159, s85, v[6:7]
	v_mad_u64_u32 v[102:103], s[44:45], v150, s85, v[6:7]
	v_mad_u64_u32 v[104:105], s[44:45], v161, s85, v[6:7]
	v_mad_u64_u32 v[106:107], s[44:45], v152, s85, v[6:7]
	v_mad_u64_u32 v[108:109], s[44:45], v163, s85, v[6:7]
	v_mad_u64_u32 v[110:111], s[44:45], v154, s85, v[6:7]
	v_mad_u64_u32 v[112:113], s[44:45], v165, s85, v[6:7]
	v_mad_u64_u32 v[114:115], s[44:45], v156, s85, v[6:7]
	v_mad_u64_u32 v[118:119], s[44:45], v167, s85, v[6:7]
	v_mad_u64_u32 v[120:121], s[44:45], v158, s85, v[6:7]
	v_mad_u64_u32 v[122:123], s[44:45], v169, s85, v[6:7]
	v_mad_u64_u32 v[124:125], s[44:45], v160, s85, v[6:7]
	v_mad_u64_u32 v[126:127], s[44:45], v183, s85, v[6:7]
	v_mad_u64_u32 v[128:129], s[44:45], v162, s85, v[6:7]
	v_mad_u64_u32 v[130:131], s[44:45], v185, s85, v[6:7]
	v_mad_u64_u32 v[132:133], s[44:45], v164, s85, v[6:7]
	s_waitcnt vmcnt(15)
	ds_write_b32 v100, v97
	s_waitcnt vmcnt(14)
	ds_write_b32 v102, v99
	s_waitcnt vmcnt(13)
	ds_write_b32 v104, v117
	s_waitcnt vmcnt(12)
	ds_write_b32 v106, v96
	s_waitcnt vmcnt(4)
	ds_write_b32 v108, v136
	ds_write_b32 v110, v135
	ds_write_b32 v112, v153
	ds_write_b32 v114, v98
	s_waitcnt vmcnt(0)
	ds_write_b32 v118, v157
	ds_write_b32 v120, v137
	ds_write_b32 v122, v138
	ds_write_b32 v124, v116
	ds_write_b32 v126, v155
	ds_write_b32 v128, v151
	ds_write_b32 v130, v94
	ds_write_b32 v132, v134
	v_readlane_b32 s3, v251, 20
	s_waitcnt lgkmcnt(0)
	s_add_u32 s3, s3, s38
	v_readlane_b32 s38, v251, 21
	s_addc_u32 s38, s38, s39
	s_lshl_b32 s2, s2, 1
	ds_read2_b32 v[14:15], v9 offset1:33
	s_add_u32 s2, s3, s2
	s_waitcnt lgkmcnt(0)
	v_cvt_pk_bf16_f32 v14, v14, v15
	ds_read2_b32 v[16:17], v9 offset0:66 offset1:99
	v_lshlrev_b32_e32 v0, 1, v8
	v_or_b32_e32 v5, s1, v7
	s_addc_u32 s3, s38, 0
	s_waitcnt lgkmcnt(0)
	v_cvt_pk_bf16_f32 v15, v16, v17
	ds_read2_b32 v[16:17], v9 offset0:132 offset1:165
	v_lshl_add_u64 v[24:25], s[2:3], 0, v[0:1]
	v_lshlrev_b32_e32 v0, 12, v5
	s_waitcnt lgkmcnt(0)
	v_cvt_pk_bf16_f32 v16, v16, v17
	ds_read2_b32 v[22:23], v9 offset0:198 offset1:231
	s_waitcnt lgkmcnt(0)
	v_cvt_pk_bf16_f32 v17, v22, v23
	v_lshl_add_u64 v[26:27], v[24:25], 0, v[0:1]
	ds_read2_b32 v[22:23], v9 offset0:8 offset1:41
	global_store_dwordx4 v[26:27], v[14:17], off sc1
	v_or_b32_e32 v0, s1, v18
	v_lshlrev_b32_e32 v0, 12, v0
	s_waitcnt lgkmcnt(0)
	v_cvt_pk_bf16_f32 v14, v22, v23
	ds_read2_b32 v[16:17], v9 offset0:74 offset1:107
	s_waitcnt lgkmcnt(0)
	v_cvt_pk_bf16_f32 v15, v16, v17
	ds_read2_b32 v[16:17], v9 offset0:140 offset1:173
	s_waitcnt lgkmcnt(0)
	v_cvt_pk_bf16_f32 v16, v16, v17
	ds_read2_b32 v[22:23], v9 offset0:206 offset1:239
	s_waitcnt lgkmcnt(0)
	v_cvt_pk_bf16_f32 v17, v22, v23
	v_lshl_add_u64 v[26:27], v[24:25], 0, v[0:1]
	ds_read2_b32 v[22:23], v9 offset0:16 offset1:49
	global_store_dwordx4 v[26:27], v[14:17], off sc1
	v_or_b32_e32 v0, s1, v19
	v_lshlrev_b32_e32 v0, 12, v0
	s_waitcnt lgkmcnt(0)
	v_cvt_pk_bf16_f32 v14, v22, v23
	ds_read2_b32 v[16:17], v9 offset0:82 offset1:115
	s_waitcnt lgkmcnt(0)
	v_cvt_pk_bf16_f32 v15, v16, v17
	ds_read2_b32 v[16:17], v9 offset0:148 offset1:181
	s_waitcnt lgkmcnt(0)
	v_cvt_pk_bf16_f32 v16, v16, v17
	ds_read2_b32 v[22:23], v9 offset0:214 offset1:247
	s_waitcnt lgkmcnt(0)
	v_cvt_pk_bf16_f32 v17, v22, v23
	v_lshl_add_u64 v[26:27], v[24:25], 0, v[0:1]
	ds_read2_b32 v[22:23], v9 offset0:24 offset1:57
	global_store_dwordx4 v[26:27], v[14:17], off sc1
	v_or_b32_e32 v0, s1, v20
	v_lshlrev_b32_e32 v0, 12, v0
	s_waitcnt lgkmcnt(0)
	v_cvt_pk_bf16_f32 v14, v22, v23
	ds_read2_b32 v[16:17], v9 offset0:90 offset1:123
	s_waitcnt lgkmcnt(0)
	v_cvt_pk_bf16_f32 v15, v16, v17
	ds_read2_b32 v[16:17], v9 offset0:156 offset1:189
	s_waitcnt lgkmcnt(0)
	v_cvt_pk_bf16_f32 v16, v16, v17
	ds_read2_b32 v[22:23], v9 offset0:222 offset1:255
	s_waitcnt lgkmcnt(0)
	v_cvt_pk_bf16_f32 v17, v22, v23
	v_lshl_add_u64 v[22:23], v[24:25], 0, v[0:1]
	global_store_dwordx4 v[22:23], v[14:17], off sc1
	s_waitcnt lgkmcnt(0)
	s_mov_b32 s48, 0x3a000000

; #define LDS_WAIT() asm volatile("s_waitcnt lgkmcnt(0)" ::: "memory")
;     ...
; #pragma unroll 8
;     for (int i = 0; i < 32; ++i) { const int kk = 2 * i + (lane >> 5); scr[kk * 33 + (lane & 31)] = W[(size_t)(k0 + kk) * N + n0 + (lane & 31)]; }
;     LDS_WAIT(); asm volatile("" ::: "memory");
.LBB0_498:
	s_lshl_b32 s41, s2, 1
	s_lshl_b32 s43, s3, 1
	v_or_b32_e32 v21, s41, v5
	v_or_b32_e32 v16, s43, v0
	s_add_i32 s46, s41, 4
	s_add_i32 s47, s43, 4
	s_add_i32 s48, s41, 8
	s_add_i32 s49, s43, 8
	s_add_i32 s50, s41, 12
	s_add_i32 s51, s43, 12
	s_add_i32 s52, s41, 16
	s_add_i32 s53, s43, 16
	s_add_i32 s54, s41, 20
	s_add_i32 s55, s43, 20
	s_add_i32 s56, s41, 24
	s_add_i32 s57, s43, 24
	s_add_i32 s58, s41, 28
	s_add_i32 s59, s43, 28
	v_mad_i64_i32 v[16:17], s[44:45], v16, s6, v[14:15]
	v_mad_i64_i32 v[22:23], s[44:45], v21, s6, v[14:15]
	v_or_b32_e32 v21, s46, v5
	v_or_b32_e32 v24, s47, v0
	v_or_b32_e32 v30, s48, v5
	v_or_b32_e32 v28, s49, v0
	v_or_b32_e32 v34, s50, v5
	v_or_b32_e32 v32, s51, v0
	v_or_b32_e32 v39, s52, v5
	v_or_b32_e32 v36, s53, v0
	v_or_b32_e32 v44, s54, v5
	v_or_b32_e32 v42, s55, v0
	v_or_b32_e32 v48, s56, v5
	v_or_b32_e32 v46, s57, v0
	v_or_b32_e32 v52, s58, v5
	v_or_b32_e32 v50, s59, v0
	v_mad_i64_i32 v[24:25], s[44:45], v24, s6, v[14:15]
	v_mad_i64_i32 v[26:27], s[44:45], v21, s6, v[14:15]
	v_mad_i64_i32 v[28:29], s[44:45], v28, s6, v[14:15]
	v_mad_i64_i32 v[30:31], s[44:45], v30, s6, v[14:15]
	v_mad_i64_i32 v[32:33], s[44:45], v32, s6, v[14:15]
	v_mad_i64_i32 v[34:35], s[44:45], v34, s6, v[14:15]
	v_mad_i64_i32 v[36:37], s[44:45], v36, s6, v[14:15]
	v_mad_i64_i32 v[40:41], s[44:45], v39, s6, v[14:15]
	v_mad_i64_i32 v[42:43], s[44:45], v42, s6, v[14:15]
	v_mad_i64_i32 v[44:45], s[44:45], v44, s6, v[14:15]
	v_mad_i64_i32 v[46:47], s[44:45], v46, s6, v[14:15]
	v_mad_i64_i32 v[48:49], s[44:45], v48, s6, v[14:15]
	v_mad_i64_i32 v[50:51], s[44:45], v50, s6, v[14:15]
	v_mad_i64_i32 v[52:53], s[44:45], v52, s6, v[14:15]
	global_load_dword v21, v[16:17], off nt
	global_load_dword v39, v[22:23], off nt
	global_load_dword v54, v[24:25], off nt
	global_load_dword v55, v[26:27], off nt
	global_load_dword v56, v[28:29], off nt
	global_load_dword v57, v[30:31], off nt
	global_load_dword v58, v[32:33], off nt
	global_load_dword v59, v[34:35], off nt
	global_load_dword v60, v[36:37], off nt
	global_load_dword v61, v[40:41], off nt
	global_load_dword v62, v[42:43], off nt
	global_load_dword v63, v[44:45], off nt
	global_load_dword v64, v[46:47], off nt
	global_load_dword v65, v[48:49], off nt
	global_load_dword v66, v[50:51], off nt
	global_load_dword v67, v[52:53], off nt
	v_or_b32_e32 v214, s41, v3
	v_or_b32_e32 v215, s43, v2
	v_or_b32_e32 v216, s46, v3
	v_or_b32_e32 v217, s47, v2
	v_or_b32_e32 v218, s48, v3
	v_or_b32_e32 v219, s49, v2
	v_or_b32_e32 v220, s50, v3
	v_or_b32_e32 v221, s51, v2
	v_or_b32_e32 v222, s52, v3
	v_or_b32_e32 v223, s53, v2
	v_or_b32_e32 v224, s54, v3
	v_or_b32_e32 v225, s55, v2
	v_or_b32_e32 v226, s56, v3
	v_or_b32_e32 v227, s57, v2
	v_or_b32_e32 v228, s58, v3
	v_or_b32_e32 v229, s59, v2
	s_add_i32 s3, s3, 16
	s_add_i32 s2, s2, 16
	s_add_i32 s39, s39, -16
	s_cmp_lg_u32 s39, 0
	s_lshl_b32 s41, s2, 1
	s_lshl_b32 s43, s3, 1
	v_or_b32_e32 v97, s41, v5
	v_or_b32_e32 v94, s43, v0
	s_add_i32 s46, s41, 4
	s_add_i32 s47, s43, 4
	s_add_i32 s48, s41, 8
	s_add_i32 s49, s43, 8
	s_add_i32 s50, s41, 12
	s_add_i32 s51, s43, 12
	s_add_i32 s52, s41, 16
	s_add_i32 s53, s43, 16
	s_add_i32 s54, s41, 20
	s_add_i32 s55, s43, 20
	s_add_i32 s56, s41, 24
	s_add_i32 s57, s43, 24
	s_add_i32 s58, s41, 28
	s_add_i32 s59, s43, 28
	v_mad_i64_i32 v[94:95], s[44:45], v94, s6, v[14:15]
	v_mad_i64_i32 v[98:99], s[44:45], v97, s6, v[14:15]
	v_or_b32_e32 v97, s46, v5
	v_or_b32_e32 v100, s47, v0
	v_or_b32_e32 v106, s48, v5
	v_or_b32_e32 v104, s49, v0
	v_or_b32_e32 v110, s50, v5
	v_or_b32_e32 v108, s51, v0
	v_or_b32_e32 v115, s52, v5
	v_or_b32_e32 v112, s53, v0
	v_or_b32_e32 v120, s54, v5
	v_or_b32_e32 v118, s55, v0
	v_or_b32_e32 v124, s56, v5
	v_or_b32_e32 v122, s57, v0
	v_or_b32_e32 v128, s58, v5
	v_or_b32_e32 v126, s59, v0
	v_mad_i64_i32 v[100:101], s[44:45], v100, s6, v[14:15]
	v_mad_i64_i32 v[102:103], s[44:45], v97, s6, v[14:15]
	v_mad_i64_i32 v[104:105], s[44:45], v104, s6, v[14:15]
	v_mad_i64_i32 v[106:107], s[44:45], v106, s6, v[14:15]
	v_mad_i64_i32 v[108:109], s[44:45], v108, s6, v[14:15]
	v_mad_i64_i32 v[110:111], s[44:45], v110, s6, v[14:15]
	v_mad_i64_i32 v[112:113], s[44:45], v112, s6, v[14:15]
	v_mad_i64_i32 v[116:117], s[44:45], v115, s6, v[14:15]
	v_mad_i64_i32 v[118:119], s[44:45], v118, s6, v[14:15]
	v_mad_i64_i32 v[120:121], s[44:45], v120, s6, v[14:15]
	v_mad_i64_i32 v[122:123], s[44:45], v122, s6, v[14:15]
	v_mad_i64_i32 v[124:125], s[44:45], v124, s6, v[14:15]
	v_mad_i64_i32 v[126:127], s[44:45], v126, s6, v[14:15]
	v_mad_i64_i32 v[128:129], s[44:45], v128, s6, v[14:15]
	global_load_dword v97, v[94:95], off nt
	global_load_dword v115, v[98:99], off nt
	global_load_dword v96, v[100:101], off nt
	global_load_dword v131, v[102:103], off nt
	global_load_dword v114, v[104:105], off nt
	global_load_dword v133, v[106:107], off nt
	global_load_dword v130, v[108:109], off nt
	global_load_dword v135, v[110:111], off nt
	global_load_dword v132, v[112:113], off nt
	global_load_dword v137, v[116:117], off nt
	global_load_dword v134, v[118:119], off nt
	global_load_dword v151, v[120:121], off nt
	global_load_dword v136, v[122:123], off nt
	global_load_dword v153, v[124:125], off nt
	global_load_dword v138, v[126:127], off nt
	global_load_dword v155, v[128:129], off nt
	v_or_b32_e32 v150, s41, v3
	v_or_b32_e32 v157, s43, v2
	v_or_b32_e32 v152, s46, v3
	v_or_b32_e32 v159, s47, v2
	v_or_b32_e32 v154, s48, v3
	v_or_b32_e32 v161, s49, v2
	v_or_b32_e32 v156, s50, v3
	v_or_b32_e32 v163, s51, v2
	v_or_b32_e32 v158, s52, v3
	v_or_b32_e32 v165, s53, v2
	v_or_b32_e32 v160, s54, v3
	v_or_b32_e32 v167, s55, v2
	v_or_b32_e32 v162, s56, v3
	v_or_b32_e32 v169, s57, v2
	v_or_b32_e32 v164, s58, v3
	v_or_b32_e32 v183, s59, v2
	s_add_i32 s3, s3, 16
	s_add_i32 s2, s2, 16
	s_add_i32 s39, s39, -16
	s_cmp_lg_u32 s39, 0
	v_mad_u64_u32 v[16:17], s[44:45], v215, s85, v[6:7]
	v_mad_u64_u32 v[22:23], s[44:45], v214, s85, v[6:7]
	v_mad_u64_u32 v[24:25], s[44:45], v217, s85, v[6:7]
	v_mad_u64_u32 v[26:27], s[44:45], v216, s85, v[6:7]
	v_mad_u64_u32 v[28:29], s[44:45], v219, s85, v[6:7]
	v_mad_u64_u32 v[30:31], s[44:45], v218, s85, v[6:7]
	v_mad_u64_u32 v[32:33], s[44:45], v221, s85, v[6:7]
	v_mad_u64_u32 v[34:35], s[44:45], v220, s85, v[6:7]
	v_mad_u64_u32 v[36:37], s[44:45], v223, s85, v[6:7]
	v_mad_u64_u32 v[40:41], s[44:45], v222, s85, v[6:7]
	v_mad_u64_u32 v[42:43], s[44:45], v225, s85, v[6:7]
	v_mad_u64_u32 v[44:45], s[44:45], v224, s85, v[6:7]
	v_mad_u64_u32 v[46:47], s[44:45], v227, s85, v[6:7]
	v_mad_u64_u32 v[48:49], s[44:45], v226, s85, v[6:7]
	v_mad_u64_u32 v[50:51], s[44:45], v229, s85, v[6:7]
	v_mad_u64_u32 v[52:53], s[44:45], v228, s85, v[6:7]
	s_waitcnt vmcnt(31)
; __device__ __forceinline__ unsigned cvt_pk_bf16(float lo, float hi) { unsigned r; asm volatile("v_cvt_pk_bf16_f32 %0, %1, %2" : "=v"(r) : "v"(lo), "v"(hi)); return r; }
; #define LAS __attribute__((address_space(3)))
; #define LDS_WAIT() asm volatile("s_waitcnt lgkmcnt(0)" ::: "memory")
;     ...
;     for (int i = 0; i < 32; ++i) { const int kk = 2 * i + (lane >> 5); scr[kk * 33 + (lane & 31)] = W[(size_t)(k0 + kk) * N + n0 + (lane & 31)]; }
;     LDS_WAIT(); asm volatile("" ::: "memory");
;     const int c = lane & 7;
; #pragma unroll
;     for (int j = 0; j < 4; ++j) { const int n = (lane >> 3) + 8 * j; const LAS float* s = scr + (8 * c) * 33 + n;
;         u32x4 o; o.x = cvt_pk_bf16(s[0 * 33], s[1 * 33]); o.y = cvt_pk_bf16(s[2 * 33], s[3 * 33]); o.z = cvt_pk_bf16(s[4 * 33], s[5 * 33]); o.w = cvt_pk_bf16(s[6 * 33], s[7 * 33]);
;         *(u32x4*)(WT + (size_t)(dn0 + n) * ldo + koff + k0 + 8 * c) = o; }
;     LDS_WAIT(); asm volatile("" ::: "memory");
	ds_write_b32 v16, v21
	s_waitcnt vmcnt(30)
	ds_write_b32 v22, v39
	s_waitcnt vmcnt(29)
	ds_write_b32 v24, v54
	s_waitcnt vmcnt(28)
	ds_write_b32 v26, v55
	s_waitcnt vmcnt(27)
	ds_write_b32 v28, v56
	s_waitcnt vmcnt(26)
	ds_write_b32 v30, v57
	s_waitcnt vmcnt(25)
	ds_write_b32 v32, v58
	s_waitcnt vmcnt(24)
	ds_write_b32 v34, v59
	s_waitcnt vmcnt(23)
	ds_write_b32 v36, v60
	s_waitcnt vmcnt(22)
	ds_write_b32 v40, v61
	s_waitcnt vmcnt(21)
	ds_write_b32 v42, v62
	s_waitcnt vmcnt(20)
	ds_write_b32 v44, v63
	s_waitcnt vmcnt(19)
	ds_write_b32 v46, v64
	s_waitcnt vmcnt(18)
	ds_write_b32 v48, v65
	s_waitcnt vmcnt(17)
	ds_write_b32 v50, v66
	s_waitcnt vmcnt(16)
	ds_write_b32 v52, v67
	v_mad_u64_u32 v[94:95], s[44:45], v157, s85, v[6:7]
	v_mad_u64_u32 v[98:99], s[44:45], v150, s85, v[6:7]
	v_mad_u64_u32 v[100:101], s[44:45], v159, s85, v[6:7]
	v_mad_u64_u32 v[102:103], s[44:45], v152, s85, v[6:7]
	v_mad_u64_u32 v[104:105], s[44:45], v161, s85, v[6:7]
	v_mad_u64_u32 v[106:107], s[44:45], v154, s85, v[6:7]
	v_mad_u64_u32 v[108:109], s[44:45], v163, s85, v[6:7]
	v_mad_u64_u32 v[110:111], s[44:45], v156, s85, v[6:7]
	v_mad_u64_u32 v[112:113], s[44:45], v165, s85, v[6:7]
	v_mad_u64_u32 v[116:117], s[44:45], v158, s85, v[6:7]
	v_mad_u64_u32 v[118:119], s[44:45], v167, s85, v[6:7]
	v_mad_u64_u32 v[120:121], s[44:45], v160, s85, v[6:7]
	v_mad_u64_u32 v[122:123], s[44:45], v169, s85, v[6:7]
	v_mad_u64_u32 v[124:125], s[44:45], v162, s85, v[6:7]
	v_mad_u64_u32 v[126:127], s[44:45], v183, s85, v[6:7]
	v_mad_u64_u32 v[128:129], s[44:45], v164, s85, v[6:7]
	s_waitcnt vmcnt(15)
	ds_write_b32 v94, v97
	s_waitcnt vmcnt(14)
	ds_write_b32 v98, v115
	s_waitcnt vmcnt(13)
	ds_write_b32 v100, v96
	s_waitcnt vmcnt(12)
	ds_write_b32 v102, v131
	s_waitcnt vmcnt(11)
	ds_write_b32 v104, v114
	s_waitcnt vmcnt(10)
	ds_write_b32 v106, v133
	s_waitcnt vmcnt(9)
	ds_write_b32 v108, v130
	s_waitcnt vmcnt(8)
	ds_write_b32 v110, v135
	s_waitcnt vmcnt(7)
	ds_write_b32 v112, v132
	s_waitcnt vmcnt(6)
	ds_write_b32 v116, v137
	s_waitcnt vmcnt(5)
	ds_write_b32 v118, v134
	s_waitcnt vmcnt(4)
	ds_write_b32 v120, v151
	s_waitcnt vmcnt(3)
	ds_write_b32 v122, v136
	s_waitcnt vmcnt(2)
	ds_write_b32 v124, v153
	s_waitcnt vmcnt(1)
	ds_write_b32 v126, v138
	s_waitcnt vmcnt(0)
	ds_write_b32 v128, v155
	s_waitcnt lgkmcnt(0)
	s_mul_hi_i32 s2, s0, 0x3100000
	s_mul_i32 s0, s0, 0x3100000
	s_add_u32 s3, s91, s0
	ds_read2_b32 v[14:15], v9 offset1:33
	s_addc_u32 s2, s93, s2
	s_waitcnt lgkmcnt(0)
	v_cvt_pk_bf16_f32 v14, v14, v15
	ds_read2_b32 v[16:17], v9 offset0:66 offset1:99
	s_cmpk_lt_i32 s1, 0x64
	s_waitcnt lgkmcnt(0)
	v_cvt_pk_bf16_f32 v15, v16, v17
	ds_read2_b32 v[16:17], v9 offset0:132 offset1:165
	s_cselect_b32 s0, 0, 0x80
	s_ashr_i32 s39, s38, 31
	s_add_i32 s40, s0, s40
	s_waitcnt lgkmcnt(0)
	v_cvt_pk_bf16_f32 v16, v16, v17
	ds_read2_b32 v[22:23], v9 offset0:198 offset1:231
	s_lshl_b64 s[0:1], s[38:39], 1
	s_add_u32 s0, s3, s0
	s_waitcnt lgkmcnt(0)
	v_cvt_pk_bf16_f32 v17, v22, v23
	v_or_b32_e32 v22, s40, v7
	v_lshlrev_b32_e32 v0, 1, v8
	s_addc_u32 s1, s2, s1
	v_ashrrev_i32_e32 v23, 31, v22
	v_lshl_add_u64 v[24:25], s[0:1], 0, v[0:1]
	v_lshlrev_b64 v[22:23], 12, v[22:23]
	ds_read2_b32 v[26:27], v9 offset0:8 offset1:41
	v_lshl_add_u64 v[22:23], v[24:25], 0, v[22:23]
	global_store_dwordx4 v[22:23], v[14:17], off sc1
	s_mov_b32 s48, 0x3a000000
	s_waitcnt lgkmcnt(0)
	v_cvt_pk_bf16_f32 v14, v26, v27
	v_or_b32_e32 v26, s40, v18
	v_ashrrev_i32_e32 v27, 31, v26
	ds_read2_b32 v[16:17], v9 offset0:74 offset1:107
	v_lshlrev_b64 v[26:27], 12, v[26:27]
	s_waitcnt lgkmcnt(0)
	v_cvt_pk_bf16_f32 v15, v16, v17
	ds_read2_b32 v[16:17], v9 offset0:140 offset1:173
	v_lshl_add_u64 v[26:27], v[24:25], 0, v[26:27]
	s_waitcnt lgkmcnt(0)
	v_cvt_pk_bf16_f32 v16, v16, v17
	ds_read2_b32 v[22:23], v9 offset0:206 offset1:239
	s_waitcnt lgkmcnt(0)
	v_cvt_pk_bf16_f32 v17, v22, v23
	global_store_dwordx4 v[26:27], v[14:17], off sc1
	v_or_b32_e32 v26, s40, v19
	ds_read2_b32 v[22:23], v9 offset0:16 offset1:49
	s_waitcnt lgkmcnt(0)
	v_cvt_pk_bf16_f32 v14, v22, v23
	ds_read2_b32 v[16:17], v9 offset0:82 offset1:115
	v_ashrrev_i32_e32 v27, 31, v26
	s_waitcnt lgkmcnt(0)
	v_cvt_pk_bf16_f32 v15, v16, v17
	ds_read2_b32 v[16:17], v9 offset0:148 offset1:181
	v_lshlrev_b64 v[26:27], 12, v[26:27]
	s_waitcnt lgkmcnt(0)
	v_cvt_pk_bf16_f32 v16, v16, v17
	ds_read2_b32 v[22:23], v9 offset0:214 offset1:247
	s_waitcnt lgkmcnt(0)
	v_cvt_pk_bf16_f32 v17, v22, v23
	v_lshl_add_u64 v[26:27], v[24:25], 0, v[26:27]
	ds_read2_b32 v[22:23], v9 offset0:24 offset1:57
	global_store_dwordx4 v[26:27], v[14:17], off sc1
	v_or_b32_e32 v26, s40, v20
	v_ashrrev_i32_e32 v27, 31, v26
	s_waitcnt lgkmcnt(0)
	v_cvt_pk_bf16_f32 v14, v22, v23
	ds_read2_b32 v[16:17], v9 offset0:90 offset1:123
	s_waitcnt lgkmcnt(0)
	v_cvt_pk_bf16_f32 v15, v16, v17
	ds_read2_b32 v[16:17], v9 offset0:156 offset1:189
	s_waitcnt lgkmcnt(0)
	v_cvt_pk_bf16_f32 v16, v16, v17
	ds_read2_b32 v[22:23], v9 offset0:222 offset1:255
	v_lshlrev_b64 v[26:27], 12, v[26:27]
	s_waitcnt lgkmcnt(0)
	v_cvt_pk_bf16_f32 v17, v22, v23
	v_lshl_add_u64 v[22:23], v[24:25], 0, v[26:27]
	global_store_dwordx4 v[22:23], v[14:17], off sc1
	s_waitcnt lgkmcnt(0)
	s_branch .LBB0_467
